# all 5 GEMM K-loops: first iteration peeled with C=0 on each accumulator's first MFMA, the 128 v_mov accumulator zeroing per unit removed
# speedup vs baseline: 1.0203x; 1.0010x over previous
.LBB0_215:
	s_ashr_i32 s65, s64, 31
	s_lshl_b64 s[34:35], s[64:65], 19
	s_add_u32 s74, s62, s34
	s_addc_u32 s75, s63, s35
	s_and_b64 s[34:35], s[36:37], exec
	s_cselect_b32 s9, s75, s91
	s_cselect_b32 s34, s74, s90
	s_ashr_i32 s41, s40, 31
	s_lshl_b64 s[72:73], s[40:41], 19
	v_readlane_b32 s10, v252, 23
	s_add_u32 s76, s10, s72
	v_readlane_b32 s10, v252, 24
	s_addc_u32 s77, s10, s73
	s_and_b64 s[72:73], s[36:37], exec
	s_cselect_b32 s35, s77, s47
	s_cselect_b32 s41, s76, s46
	s_add_u32 s90, s90, 0x40080
	s_addc_u32 s91, s91, 0
	s_add_u32 s65, s46, 0x100
	s_addc_u32 s71, s47, 0
	s_mov_b32 s72, -2
	s_waitcnt vmcnt(0)
.Lgemm0_peel:
	s_add_u32 s10, s90, 0xfffc0080
	s_addc_u32 s33, s91, -1
	s_add_i32 s73, 0, 0x10000
	s_cmp_eq_u32 s72, 12
	s_cselect_b32 vcc_hi, s9, s33
	s_cselect_b32 vcc_lo, s34, s10
	v_add_u32_e32 v147, s73, v145
	s_cselect_b32 s47, s35, s71
	s_cselect_b32 s46, s41, s65
	s_add_i32 s10, 0, 0x14000
	ds_read_b128 v[140:143], v147
	ds_read_b128 v[148:151], v147 offset:1024
	ds_read_b128 v[152:155], v147 offset:2048
	ds_read_b128 v[156:159], v147 offset:3072
	v_add_u32_e32 v147, s10, v145
	ds_read_b128 v[160:163], v147
	ds_read_b128 v[164:167], v147 offset:1024
	ds_read_b128 v[168:171], v147 offset:2048
	ds_read_b128 v[172:175], v147 offset:3072
	v_lshl_add_u64 v[240:241], s[90:91], 0, v[136:137]
	s_add_i32 m0, s11, 0xc000
	ds_read_b128 v[176:179], v146
	ds_read_b128 v[180:183], v146 offset:1024
	ds_read_b128 v[184:187], v146 offset:2048
	ds_read_b128 v[208:211], v146 offset:3072
	ds_read_b128 v[212:215], v146 offset:4096
	ds_read_b128 v[228:231], v146 offset:5120
	ds_read_b128 v[232:235], v146 offset:6144
	ds_read_b128 v[236:239], v146 offset:7168
	global_load_lds_dwordx4 v[240:241], off
	v_lshl_add_u64 v[240:241], s[90:91], 0, v[138:139]
	s_add_i32 m0, s11, 0xe000
	s_nop 0
	global_load_lds_dwordx4 v[240:241], off
	s_waitcnt vmcnt(8)
	s_waitcnt lgkmcnt(0)
	s_barrier
	s_setprio 1
	s_waitcnt lgkmcnt(0)
	v_mfma_f32_16x16x32_bf16 v[124:127], v[140:143], v[176:179], 0
	v_mfma_f32_16x16x32_bf16 v[120:123], v[152:155], v[176:179], 0
	v_mfma_f32_16x16x32_bf16 v[108:111], v[140:143], v[184:187], 0
	v_mfma_f32_16x16x32_bf16 v[104:107], v[152:155], v[184:187], 0
	v_mfma_f32_16x16x32_bf16 v[92:95], v[140:143], v[212:215], 0
	v_mfma_f32_16x16x32_bf16 v[88:91], v[152:155], v[212:215], 0
	v_mfma_f32_16x16x32_bf16 v[76:79], v[140:143], v[232:235], 0
	v_mfma_f32_16x16x32_bf16 v[72:75], v[152:155], v[232:235], 0
	v_mfma_f32_16x16x32_bf16 v[124:127], v[148:151], v[180:183], v[124:127]
	v_mfma_f32_16x16x32_bf16 v[120:123], v[156:159], v[180:183], v[120:123]
	v_mfma_f32_16x16x32_bf16 v[108:111], v[148:151], v[208:211], v[108:111]
	v_mfma_f32_16x16x32_bf16 v[104:107], v[156:159], v[208:211], v[104:107]
	v_mfma_f32_16x16x32_bf16 v[92:95], v[148:151], v[228:231], v[92:95]
	v_mfma_f32_16x16x32_bf16 v[88:91], v[156:159], v[228:231], v[88:91]
	v_mfma_f32_16x16x32_bf16 v[76:79], v[148:151], v[236:239], v[76:79]
	v_mfma_f32_16x16x32_bf16 v[72:75], v[156:159], v[236:239], v[72:75]
	s_setprio 0
	s_setprio 1
	v_mfma_f32_16x16x32_bf16 v[116:119], v[160:163], v[176:179], 0
	v_mfma_f32_16x16x32_bf16 v[112:115], v[168:171], v[176:179], 0
	v_mfma_f32_16x16x32_bf16 v[100:103], v[160:163], v[184:187], 0
	v_mfma_f32_16x16x32_bf16 v[96:99], v[168:171], v[184:187], 0
	v_mfma_f32_16x16x32_bf16 v[84:87], v[160:163], v[212:215], 0
	v_mfma_f32_16x16x32_bf16 v[80:83], v[168:171], v[212:215], 0
	v_mfma_f32_16x16x32_bf16 v[68:71], v[160:163], v[232:235], 0
	v_mfma_f32_16x16x32_bf16 v[64:67], v[168:171], v[232:235], 0
	v_mfma_f32_16x16x32_bf16 v[116:119], v[164:167], v[180:183], v[116:119]
	v_mfma_f32_16x16x32_bf16 v[112:115], v[172:175], v[180:183], v[112:115]
	v_mfma_f32_16x16x32_bf16 v[100:103], v[164:167], v[208:211], v[100:103]
	v_mfma_f32_16x16x32_bf16 v[96:99], v[172:175], v[208:211], v[96:99]
	v_mfma_f32_16x16x32_bf16 v[84:87], v[164:167], v[228:231], v[84:87]
	v_mfma_f32_16x16x32_bf16 v[80:83], v[172:175], v[228:231], v[80:83]
	v_mfma_f32_16x16x32_bf16 v[68:71], v[164:167], v[236:239], v[68:71]
	v_mfma_f32_16x16x32_bf16 v[64:67], v[172:175], v[236:239], v[64:67]
	s_setprio 0
	s_barrier
	s_add_i32 s33, s73, s3
	v_lshl_add_u64 v[240:241], s[46:47], 0, v[132:133]
	s_mov_b32 m0, s33
	ds_read_b128 v[176:179], v146 offset:16384
	ds_read_b128 v[180:183], v146 offset:17408
	ds_read_b128 v[184:187], v146 offset:18432
	ds_read_b128 v[208:211], v146 offset:19456
	ds_read_b128 v[212:215], v146 offset:20480
	ds_read_b128 v[228:231], v146 offset:21504
	ds_read_b128 v[232:235], v146 offset:22528
	ds_read_b128 v[236:239], v146 offset:23552
	global_load_lds_dwordx4 v[240:241], off
	s_add_i32 m0, s33, 0x2000
	s_add_u32 s78, s46, 0x40000
	v_lshl_add_u64 v[242:243], s[46:47], 0, v[128:129]
	s_addc_u32 s79, s47, 0
	s_add_i32 s10, s10, s3
	global_load_lds_dwordx4 v[242:243], off
	v_lshl_add_u64 v[244:245], s[78:79], 0, v[132:133]
	s_mov_b32 m0, s10
	v_lshl_add_u64 v[246:247], vcc, 0, v[130:131]
	global_load_lds_dwordx4 v[244:245], off
	v_lshl_add_u64 v[244:245], s[78:79], 0, v[128:129]
	s_add_i32 m0, s10, 0x2000
	s_nop 0
	global_load_lds_dwordx4 v[244:245], off
	v_lshl_add_u64 v[244:245], vcc, 0, v[134:135]
	s_mov_b32 m0, s11
	s_nop 0
	global_load_lds_dwordx4 v[244:245], off
	s_mov_b32 m0, s12
	s_nop 0
	global_load_lds_dwordx4 v[246:247], off
	s_waitcnt vmcnt(8)
	s_waitcnt lgkmcnt(0)
	s_barrier
	s_setprio 1
	s_waitcnt lgkmcnt(0)
	v_mfma_f32_16x16x32_bf16 v[60:63], v[140:143], v[176:179], 0
	v_mfma_f32_16x16x32_bf16 v[56:59], v[152:155], v[176:179], 0
	v_mfma_f32_16x16x32_bf16 v[44:47], v[140:143], v[184:187], 0
	v_mfma_f32_16x16x32_bf16 v[40:43], v[152:155], v[184:187], 0
	v_mfma_f32_16x16x32_bf16 v[28:31], v[140:143], v[212:215], 0
	v_mfma_f32_16x16x32_bf16 v[24:27], v[152:155], v[212:215], 0
	v_mfma_f32_16x16x32_bf16 v[12:15], v[140:143], v[232:235], 0
	v_mfma_f32_16x16x32_bf16 v[8:11], v[152:155], v[232:235], 0
	v_mfma_f32_16x16x32_bf16 v[60:63], v[148:151], v[180:183], v[60:63]
	v_mfma_f32_16x16x32_bf16 v[56:59], v[156:159], v[180:183], v[56:59]
	v_mfma_f32_16x16x32_bf16 v[44:47], v[148:151], v[208:211], v[44:47]
	v_mfma_f32_16x16x32_bf16 v[40:43], v[156:159], v[208:211], v[40:43]
	v_mfma_f32_16x16x32_bf16 v[28:31], v[148:151], v[228:231], v[28:31]
	v_mfma_f32_16x16x32_bf16 v[24:27], v[156:159], v[228:231], v[24:27]
	v_mfma_f32_16x16x32_bf16 v[12:15], v[148:151], v[236:239], v[12:15]
	v_mfma_f32_16x16x32_bf16 v[8:11], v[156:159], v[236:239], v[8:11]
	s_setprio 0
	s_setprio 1
	v_mfma_f32_16x16x32_bf16 v[52:55], v[160:163], v[176:179], 0
	v_mfma_f32_16x16x32_bf16 v[48:51], v[168:171], v[176:179], 0
	v_mfma_f32_16x16x32_bf16 v[36:39], v[160:163], v[184:187], 0
	v_mfma_f32_16x16x32_bf16 v[32:35], v[168:171], v[184:187], 0
	v_mfma_f32_16x16x32_bf16 v[20:23], v[160:163], v[212:215], 0
	v_mfma_f32_16x16x32_bf16 v[16:19], v[168:171], v[212:215], 0
	v_mfma_f32_16x16x32_bf16 v[4:7], v[160:163], v[232:235], 0
	v_mfma_f32_16x16x32_bf16 v[0:3], v[168:171], v[232:235], 0
	v_mfma_f32_16x16x32_bf16 v[52:55], v[164:167], v[180:183], v[52:55]
	v_mfma_f32_16x16x32_bf16 v[48:51], v[172:175], v[180:183], v[48:51]
	v_mfma_f32_16x16x32_bf16 v[36:39], v[164:167], v[208:211], v[36:39]
	v_mfma_f32_16x16x32_bf16 v[32:35], v[172:175], v[208:211], v[32:35]
	v_mfma_f32_16x16x32_bf16 v[20:23], v[164:167], v[228:231], v[20:23]
	v_mfma_f32_16x16x32_bf16 v[16:19], v[172:175], v[228:231], v[16:19]
	v_mfma_f32_16x16x32_bf16 v[4:7], v[164:167], v[236:239], v[4:7]
	v_mfma_f32_16x16x32_bf16 v[0:3], v[172:175], v[236:239], v[0:3]
	s_setprio 0
	s_barrier
	s_add_i32 s10, 0, 0x18000
	v_add_u32_e32 v147, s10, v145
	s_add_i32 s33, 0, 0x1c000
	ds_read_b128 v[140:143], v147
	ds_read_b128 v[148:151], v147 offset:1024
	ds_read_b128 v[152:155], v147 offset:2048
	ds_read_b128 v[156:159], v147 offset:3072
	v_add_u32_e32 v147, s33, v145
	ds_read_b128 v[160:163], v147
	ds_read_b128 v[164:167], v147 offset:1024
	ds_read_b128 v[168:171], v147 offset:2048
	ds_read_b128 v[172:175], v147 offset:3072
	s_add_u32 s78, vcc_lo, 0x40000
	s_addc_u32 s79, vcc_hi, 0
	s_mov_b32 m0, s16
	v_lshl_add_u64 v[248:249], s[78:79], 0, v[134:135]
	ds_read_b128 v[176:179], v146 offset:32768
	ds_read_b128 v[180:183], v146 offset:33792
	ds_read_b128 v[184:187], v146 offset:34816
	ds_read_b128 v[208:211], v146 offset:35840
	ds_read_b128 v[212:215], v146 offset:36864
	ds_read_b128 v[228:231], v146 offset:37888
	ds_read_b128 v[232:235], v146 offset:38912
	ds_read_b128 v[236:239], v146 offset:39936
	global_load_lds_dwordx4 v[248:249], off
	v_lshl_add_u64 v[248:249], s[78:79], 0, v[130:131]
	s_mov_b32 m0, s17
	s_nop 0
	global_load_lds_dwordx4 v[248:249], off
	s_waitcnt vmcnt(8)
	s_waitcnt lgkmcnt(0)
	s_barrier
	s_setprio 1
	s_waitcnt lgkmcnt(0)
	v_mfma_f32_16x16x32_bf16 v[124:127], v[140:143], v[176:179], v[124:127]
	v_mfma_f32_16x16x32_bf16 v[120:123], v[152:155], v[176:179], v[120:123]
	v_mfma_f32_16x16x32_bf16 v[108:111], v[140:143], v[184:187], v[108:111]
	v_mfma_f32_16x16x32_bf16 v[104:107], v[152:155], v[184:187], v[104:107]
	v_mfma_f32_16x16x32_bf16 v[92:95], v[140:143], v[212:215], v[92:95]
	v_mfma_f32_16x16x32_bf16 v[88:91], v[152:155], v[212:215], v[88:91]
	v_mfma_f32_16x16x32_bf16 v[76:79], v[140:143], v[232:235], v[76:79]
	v_mfma_f32_16x16x32_bf16 v[72:75], v[152:155], v[232:235], v[72:75]
	v_mfma_f32_16x16x32_bf16 v[124:127], v[148:151], v[180:183], v[124:127]
	v_mfma_f32_16x16x32_bf16 v[120:123], v[156:159], v[180:183], v[120:123]
	v_mfma_f32_16x16x32_bf16 v[108:111], v[148:151], v[208:211], v[108:111]
	v_mfma_f32_16x16x32_bf16 v[104:107], v[156:159], v[208:211], v[104:107]
	v_mfma_f32_16x16x32_bf16 v[92:95], v[148:151], v[228:231], v[92:95]
	v_mfma_f32_16x16x32_bf16 v[88:91], v[156:159], v[228:231], v[88:91]
	v_mfma_f32_16x16x32_bf16 v[76:79], v[148:151], v[236:239], v[76:79]
	v_mfma_f32_16x16x32_bf16 v[72:75], v[156:159], v[236:239], v[72:75]
	s_setprio 0
	s_setprio 1
	v_mfma_f32_16x16x32_bf16 v[116:119], v[160:163], v[176:179], v[116:119]
	v_mfma_f32_16x16x32_bf16 v[112:115], v[168:171], v[176:179], v[112:115]
	v_mfma_f32_16x16x32_bf16 v[100:103], v[160:163], v[184:187], v[100:103]
	v_mfma_f32_16x16x32_bf16 v[96:99], v[168:171], v[184:187], v[96:99]
	v_mfma_f32_16x16x32_bf16 v[84:87], v[160:163], v[212:215], v[84:87]
	v_mfma_f32_16x16x32_bf16 v[80:83], v[168:171], v[212:215], v[80:83]
	v_mfma_f32_16x16x32_bf16 v[68:71], v[160:163], v[232:235], v[68:71]
	v_mfma_f32_16x16x32_bf16 v[64:67], v[168:171], v[232:235], v[64:67]
	v_mfma_f32_16x16x32_bf16 v[116:119], v[164:167], v[180:183], v[116:119]
	v_mfma_f32_16x16x32_bf16 v[112:115], v[172:175], v[180:183], v[112:115]
	v_mfma_f32_16x16x32_bf16 v[100:103], v[164:167], v[208:211], v[100:103]
	v_mfma_f32_16x16x32_bf16 v[96:99], v[172:175], v[208:211], v[96:99]
	v_mfma_f32_16x16x32_bf16 v[84:87], v[164:167], v[228:231], v[84:87]
	v_mfma_f32_16x16x32_bf16 v[80:83], v[172:175], v[228:231], v[80:83]
	v_mfma_f32_16x16x32_bf16 v[68:71], v[164:167], v[236:239], v[68:71]
	v_mfma_f32_16x16x32_bf16 v[64:67], v[172:175], v[236:239], v[64:67]
	s_setprio 0
	s_barrier
	s_add_i32 s10, s10, s3
	v_lshl_add_u64 v[240:241], v[240:241], 0, s[48:49]
	s_mov_b32 m0, s10
	ds_read_b128 v[176:179], v146 offset:49152
	ds_read_b128 v[180:183], v146 offset:50176
	ds_read_b128 v[184:187], v146 offset:51200
	ds_read_b128 v[208:211], v146 offset:52224
	ds_read_b128 v[212:215], v146 offset:53248
	ds_read_b128 v[228:231], v146 offset:54272
	ds_read_b128 v[232:235], v146 offset:55296
	ds_read_b128 v[236:239], v146 offset:56320
	global_load_lds_dwordx4 v[240:241], off
	s_add_i32 m0, s10, 0x2000
	s_add_u32 s46, s46, 0x40080
	v_lshl_add_u64 v[240:241], v[242:243], 0, s[48:49]
	s_addc_u32 s47, s47, 0
	s_add_i32 s10, s33, s3
	global_load_lds_dwordx4 v[240:241], off
	v_lshl_add_u64 v[240:241], s[46:47], 0, v[132:133]
	s_mov_b32 m0, s10
	s_nop 0
	global_load_lds_dwordx4 v[240:241], off
	v_lshl_add_u64 v[240:241], s[46:47], 0, v[128:129]
	s_add_i32 m0, s10, 0x2000
	s_nop 0
	global_load_lds_dwordx4 v[240:241], off
	v_lshl_add_u64 v[240:241], v[244:245], 0, s[48:49]
	s_mov_b32 m0, s18
	s_nop 0
	global_load_lds_dwordx4 v[240:241], off
	v_lshl_add_u64 v[240:241], v[246:247], 0, s[48:49]
	s_mov_b32 m0, s45
	s_nop 0
	global_load_lds_dwordx4 v[240:241], off
	s_waitcnt vmcnt(8)
	s_waitcnt lgkmcnt(0)
	s_barrier
	s_setprio 1
	s_waitcnt lgkmcnt(0)
	v_mfma_f32_16x16x32_bf16 v[60:63], v[140:143], v[176:179], v[60:63]
	v_mfma_f32_16x16x32_bf16 v[56:59], v[152:155], v[176:179], v[56:59]
	v_mfma_f32_16x16x32_bf16 v[44:47], v[140:143], v[184:187], v[44:47]
	v_mfma_f32_16x16x32_bf16 v[40:43], v[152:155], v[184:187], v[40:43]
	v_mfma_f32_16x16x32_bf16 v[28:31], v[140:143], v[212:215], v[28:31]
	v_mfma_f32_16x16x32_bf16 v[24:27], v[152:155], v[212:215], v[24:27]
	v_mfma_f32_16x16x32_bf16 v[12:15], v[140:143], v[232:235], v[12:15]
	v_mfma_f32_16x16x32_bf16 v[8:11], v[152:155], v[232:235], v[8:11]
	v_mfma_f32_16x16x32_bf16 v[60:63], v[148:151], v[180:183], v[60:63]
	v_mfma_f32_16x16x32_bf16 v[56:59], v[156:159], v[180:183], v[56:59]
	v_mfma_f32_16x16x32_bf16 v[44:47], v[148:151], v[208:211], v[44:47]
	v_mfma_f32_16x16x32_bf16 v[40:43], v[156:159], v[208:211], v[40:43]
	v_mfma_f32_16x16x32_bf16 v[28:31], v[148:151], v[228:231], v[28:31]
	v_mfma_f32_16x16x32_bf16 v[24:27], v[156:159], v[228:231], v[24:27]
	v_mfma_f32_16x16x32_bf16 v[12:15], v[148:151], v[236:239], v[12:15]
	v_mfma_f32_16x16x32_bf16 v[8:11], v[156:159], v[236:239], v[8:11]
	s_setprio 0
	s_setprio 1
	v_mfma_f32_16x16x32_bf16 v[52:55], v[160:163], v[176:179], v[52:55]
	v_mfma_f32_16x16x32_bf16 v[48:51], v[168:171], v[176:179], v[48:51]
	v_mfma_f32_16x16x32_bf16 v[36:39], v[160:163], v[184:187], v[36:39]
	v_mfma_f32_16x16x32_bf16 v[32:35], v[168:171], v[184:187], v[32:35]
	v_mfma_f32_16x16x32_bf16 v[20:23], v[160:163], v[212:215], v[20:23]
	v_mfma_f32_16x16x32_bf16 v[16:19], v[168:171], v[212:215], v[16:19]
	v_mfma_f32_16x16x32_bf16 v[4:7], v[160:163], v[232:235], v[4:7]
	v_mfma_f32_16x16x32_bf16 v[0:3], v[168:171], v[232:235], v[0:3]
	v_mfma_f32_16x16x32_bf16 v[52:55], v[164:167], v[180:183], v[52:55]
	v_mfma_f32_16x16x32_bf16 v[48:51], v[172:175], v[180:183], v[48:51]
	v_mfma_f32_16x16x32_bf16 v[36:39], v[164:167], v[208:211], v[36:39]
	v_mfma_f32_16x16x32_bf16 v[32:35], v[172:175], v[208:211], v[32:35]
	v_mfma_f32_16x16x32_bf16 v[20:23], v[164:167], v[228:231], v[20:23]
	v_mfma_f32_16x16x32_bf16 v[16:19], v[172:175], v[228:231], v[16:19]
	v_mfma_f32_16x16x32_bf16 v[4:7], v[164:167], v[236:239], v[4:7]
	v_mfma_f32_16x16x32_bf16 v[0:3], v[172:175], v[236:239], v[0:3]
	s_setprio 0
	s_barrier
	s_add_i32 s72, s72, 2
	s_add_u32 s90, s90, 0x100
	s_addc_u32 s91, s91, 0
	s_add_u32 s65, s65, 0x100
	s_addc_u32 s71, s71, 0
	s_cmp_gt_u32 s72, 13
	s_cbranch_scc0 .LBB0_216
	s_branch .Lgemm0_exit

.Lgemm0_exit:
	s_and_b64 vcc, exec, s[38:39]
	s_cbranch_vccz .LBB0_219
	s_barrier

.LBB0_235:
	s_ashr_i32 s77, s76, 31
	s_lshl_b64 s[34:35], s[76:77], 19
	v_readlane_b32 s9, v255, 25
	s_add_u32 s90, s9, s34
	v_readlane_b32 s9, v255, 26
	s_addc_u32 s91, s9, s35
	s_and_b64 s[34:35], s[38:39], exec
	s_cselect_b32 s9, s91, s1
	s_cselect_b32 s34, s90, s0
	s_ashr_i32 s75, s74, 31
	s_lshl_b64 s[64:65], s[74:75], 19
	s_add_u32 s64, s62, s64
	s_addc_u32 s65, s63, s65
	s_and_b64 s[72:73], s[38:39], exec
	s_cselect_b32 s35, s65, s47
	s_cselect_b32 s45, s64, s46
	s_add_u32 s0, s0, 0x40080
	s_addc_u32 s1, s1, 0
	s_add_u32 s60, s46, 0x100
	s_addc_u32 s72, s47, 0
	s_mov_b32 s73, -2
	s_waitcnt vmcnt(0)
.Lgemm1_peel:
	s_add_u32 s10, s0, 0xfffc0080
	s_addc_u32 s33, s1, -1
	s_add_i32 s75, 0, 0x10000
	s_cmp_eq_u32 s73, 12
	s_cselect_b32 vcc_hi, s9, s33
	s_cselect_b32 vcc_lo, s34, s10
	v_add_u32_e32 v157, s75, v154
	s_cselect_b32 s47, s35, s72
	s_cselect_b32 s46, s45, s60
	s_add_i32 s10, 0, 0x14000
	ds_read_b128 v[140:143], v157
	ds_read_b128 v[144:147], v157 offset:1024
	ds_read_b128 v[148:151], v157 offset:2048
	ds_read_b128 v[158:161], v157 offset:3072
	v_add_u32_e32 v157, s10, v154
	ds_read_b128 v[162:165], v157
	ds_read_b128 v[166:169], v157 offset:1024
	ds_read_b128 v[170:173], v157 offset:2048
	ds_read_b128 v[174:177], v157 offset:3072
	v_lshl_add_u64 v[186:187], s[0:1], 0, v[136:137]
	s_add_i32 m0, s11, 0xc000
	ds_read_b128 v[178:181], v156
	ds_read_b128 v[182:185], v156 offset:1024
	ds_read_b128 v[208:211], v156 offset:2048
	ds_read_b128 v[212:215], v156 offset:3072
	ds_read_b128 v[228:231], v156 offset:4096
	ds_read_b128 v[232:235], v156 offset:5120
	ds_read_b128 v[236:239], v156 offset:6144
	ds_read_b128 v[240:243], v156 offset:7168
	global_load_lds_dwordx4 v[186:187], off
	v_lshl_add_u64 v[186:187], s[0:1], 0, v[138:139]
	s_add_i32 m0, s11, 0xe000
	s_nop 0
	global_load_lds_dwordx4 v[186:187], off
	s_waitcnt vmcnt(8)
	s_waitcnt lgkmcnt(0)
	s_barrier
	s_setprio 1
	s_waitcnt lgkmcnt(0)
	v_mfma_f32_16x16x32_bf16 v[124:127], v[140:143], v[178:181], 0
	v_mfma_f32_16x16x32_bf16 v[120:123], v[148:151], v[178:181], 0
	v_mfma_f32_16x16x32_bf16 v[116:119], v[140:143], v[208:211], 0
	v_mfma_f32_16x16x32_bf16 v[112:115], v[148:151], v[208:211], 0
	v_mfma_f32_16x16x32_bf16 v[108:111], v[140:143], v[228:231], 0
	v_mfma_f32_16x16x32_bf16 v[104:107], v[148:151], v[228:231], 0
	v_mfma_f32_16x16x32_bf16 v[100:103], v[140:143], v[236:239], 0
	v_mfma_f32_16x16x32_bf16 v[96:99], v[148:151], v[236:239], 0
	v_mfma_f32_16x16x32_bf16 v[124:127], v[144:147], v[182:185], v[124:127]
	v_mfma_f32_16x16x32_bf16 v[120:123], v[158:161], v[182:185], v[120:123]
	v_mfma_f32_16x16x32_bf16 v[116:119], v[144:147], v[212:215], v[116:119]
	v_mfma_f32_16x16x32_bf16 v[112:115], v[158:161], v[212:215], v[112:115]
	v_mfma_f32_16x16x32_bf16 v[108:111], v[144:147], v[232:235], v[108:111]
	v_mfma_f32_16x16x32_bf16 v[104:107], v[158:161], v[232:235], v[104:107]
	v_mfma_f32_16x16x32_bf16 v[100:103], v[144:147], v[240:243], v[100:103]
	v_mfma_f32_16x16x32_bf16 v[96:99], v[158:161], v[240:243], v[96:99]
	s_setprio 0
	s_setprio 1
	v_mfma_f32_16x16x32_bf16 v[60:63], v[162:165], v[178:181], 0
	v_mfma_f32_16x16x32_bf16 v[56:59], v[170:173], v[178:181], 0
	v_mfma_f32_16x16x32_bf16 v[52:55], v[162:165], v[208:211], 0
	v_mfma_f32_16x16x32_bf16 v[48:51], v[170:173], v[208:211], 0
	v_mfma_f32_16x16x32_bf16 v[44:47], v[162:165], v[228:231], 0
	v_mfma_f32_16x16x32_bf16 v[40:43], v[170:173], v[228:231], 0
	v_mfma_f32_16x16x32_bf16 v[36:39], v[162:165], v[236:239], 0
	v_mfma_f32_16x16x32_bf16 v[32:35], v[170:173], v[236:239], 0
	v_mfma_f32_16x16x32_bf16 v[60:63], v[166:169], v[182:185], v[60:63]
	v_mfma_f32_16x16x32_bf16 v[56:59], v[174:177], v[182:185], v[56:59]
	v_mfma_f32_16x16x32_bf16 v[52:55], v[166:169], v[212:215], v[52:55]
	v_mfma_f32_16x16x32_bf16 v[48:51], v[174:177], v[212:215], v[48:51]
	v_mfma_f32_16x16x32_bf16 v[44:47], v[166:169], v[232:235], v[44:47]
	v_mfma_f32_16x16x32_bf16 v[40:43], v[174:177], v[232:235], v[40:43]
	v_mfma_f32_16x16x32_bf16 v[36:39], v[166:169], v[240:243], v[36:39]
	v_mfma_f32_16x16x32_bf16 v[32:35], v[174:177], v[240:243], v[32:35]
	s_setprio 0
	s_barrier
	s_add_i32 s33, s75, s3
	v_lshl_add_u64 v[186:187], s[46:47], 0, v[132:133]
	s_mov_b32 m0, s33
	ds_read_b128 v[178:181], v156 offset:16384
	ds_read_b128 v[182:185], v156 offset:17408
	ds_read_b128 v[208:211], v156 offset:18432
	ds_read_b128 v[212:215], v156 offset:19456
	ds_read_b128 v[228:231], v156 offset:20480
	ds_read_b128 v[232:235], v156 offset:21504
	ds_read_b128 v[236:239], v156 offset:22528
	ds_read_b128 v[240:243], v156 offset:23552
	global_load_lds_dwordx4 v[186:187], off
	s_add_i32 m0, s33, 0x2000
	s_add_u32 s78, s46, 0x40000
	v_lshl_add_u64 v[244:245], s[46:47], 0, v[128:129]
	s_addc_u32 s79, s47, 0
	s_add_i32 s10, s10, s3
	global_load_lds_dwordx4 v[244:245], off
	v_lshl_add_u64 v[246:247], s[78:79], 0, v[132:133]
	s_mov_b32 m0, s10
	v_lshl_add_u64 v[248:249], vcc, 0, v[130:131]
	global_load_lds_dwordx4 v[246:247], off
	v_lshl_add_u64 v[246:247], s[78:79], 0, v[128:129]
	s_add_i32 m0, s10, 0x2000
	s_nop 0
	global_load_lds_dwordx4 v[246:247], off
	v_lshl_add_u64 v[246:247], vcc, 0, v[134:135]
	s_mov_b32 m0, s11
	s_nop 0
	global_load_lds_dwordx4 v[246:247], off
	s_mov_b32 m0, s12
	s_nop 0
	global_load_lds_dwordx4 v[248:249], off
	s_waitcnt vmcnt(8)
	s_waitcnt lgkmcnt(0)
	s_barrier
	s_setprio 1
	s_waitcnt lgkmcnt(0)
	v_mfma_f32_16x16x32_bf16 v[92:95], v[140:143], v[178:181], 0
	v_mfma_f32_16x16x32_bf16 v[88:91], v[148:151], v[178:181], 0
	v_mfma_f32_16x16x32_bf16 v[84:87], v[140:143], v[208:211], 0
	v_mfma_f32_16x16x32_bf16 v[80:83], v[148:151], v[208:211], 0
	v_mfma_f32_16x16x32_bf16 v[76:79], v[140:143], v[228:231], 0
	v_mfma_f32_16x16x32_bf16 v[72:75], v[148:151], v[228:231], 0
	v_mfma_f32_16x16x32_bf16 v[68:71], v[140:143], v[236:239], 0
	v_mfma_f32_16x16x32_bf16 v[64:67], v[148:151], v[236:239], 0
	v_mfma_f32_16x16x32_bf16 v[92:95], v[144:147], v[182:185], v[92:95]
	v_mfma_f32_16x16x32_bf16 v[88:91], v[158:161], v[182:185], v[88:91]
	v_mfma_f32_16x16x32_bf16 v[84:87], v[144:147], v[212:215], v[84:87]
	v_mfma_f32_16x16x32_bf16 v[80:83], v[158:161], v[212:215], v[80:83]
	v_mfma_f32_16x16x32_bf16 v[76:79], v[144:147], v[232:235], v[76:79]
	v_mfma_f32_16x16x32_bf16 v[72:75], v[158:161], v[232:235], v[72:75]
	v_mfma_f32_16x16x32_bf16 v[68:71], v[144:147], v[240:243], v[68:71]
	v_mfma_f32_16x16x32_bf16 v[64:67], v[158:161], v[240:243], v[64:67]
	s_setprio 0
	s_setprio 1
	v_mfma_f32_16x16x32_bf16 v[28:31], v[162:165], v[178:181], 0
	v_mfma_f32_16x16x32_bf16 v[24:27], v[170:173], v[178:181], 0
	v_mfma_f32_16x16x32_bf16 v[20:23], v[162:165], v[208:211], 0
	v_mfma_f32_16x16x32_bf16 v[16:19], v[170:173], v[208:211], 0
	v_mfma_f32_16x16x32_bf16 v[12:15], v[162:165], v[228:231], 0
	v_mfma_f32_16x16x32_bf16 v[8:11], v[170:173], v[228:231], 0
	v_mfma_f32_16x16x32_bf16 v[4:7], v[162:165], v[236:239], 0
	v_mfma_f32_16x16x32_bf16 v[0:3], v[170:173], v[236:239], 0
	v_mfma_f32_16x16x32_bf16 v[28:31], v[166:169], v[182:185], v[28:31]
	v_mfma_f32_16x16x32_bf16 v[24:27], v[174:177], v[182:185], v[24:27]
	v_mfma_f32_16x16x32_bf16 v[20:23], v[166:169], v[212:215], v[20:23]
	v_mfma_f32_16x16x32_bf16 v[16:19], v[174:177], v[212:215], v[16:19]
	v_mfma_f32_16x16x32_bf16 v[12:15], v[166:169], v[232:235], v[12:15]
	v_mfma_f32_16x16x32_bf16 v[8:11], v[174:177], v[232:235], v[8:11]
	v_mfma_f32_16x16x32_bf16 v[4:7], v[166:169], v[240:243], v[4:7]
	v_mfma_f32_16x16x32_bf16 v[0:3], v[174:177], v[240:243], v[0:3]
	s_setprio 0
	s_barrier
	s_add_i32 s10, 0, 0x18000
	v_add_u32_e32 v157, s10, v154
	s_add_i32 s33, 0, 0x1c000
	ds_read_b128 v[140:143], v157
	ds_read_b128 v[144:147], v157 offset:1024
	ds_read_b128 v[148:151], v157 offset:2048
	ds_read_b128 v[158:161], v157 offset:3072
	v_add_u32_e32 v157, s33, v154
	ds_read_b128 v[162:165], v157
	ds_read_b128 v[166:169], v157 offset:1024
	ds_read_b128 v[170:173], v157 offset:2048
	ds_read_b128 v[174:177], v157 offset:3072
	s_add_u32 s78, vcc_lo, 0x40000
	s_addc_u32 s79, vcc_hi, 0
	s_mov_b32 m0, s16
	v_lshl_add_u64 v[250:251], s[78:79], 0, v[134:135]
	ds_read_b128 v[178:181], v156 offset:32768
	ds_read_b128 v[182:185], v156 offset:33792
	ds_read_b128 v[208:211], v156 offset:34816
	ds_read_b128 v[212:215], v156 offset:35840
	ds_read_b128 v[228:231], v156 offset:36864
	ds_read_b128 v[232:235], v156 offset:37888
	ds_read_b128 v[236:239], v156 offset:38912
	ds_read_b128 v[240:243], v156 offset:39936
	global_load_lds_dwordx4 v[250:251], off
	v_lshl_add_u64 v[250:251], s[78:79], 0, v[130:131]
	s_mov_b32 m0, s17
	s_nop 0
	global_load_lds_dwordx4 v[250:251], off
	s_waitcnt vmcnt(8)
	s_waitcnt lgkmcnt(0)
	s_barrier
	s_setprio 1
	s_waitcnt lgkmcnt(0)
	v_mfma_f32_16x16x32_bf16 v[124:127], v[140:143], v[178:181], v[124:127]
	v_mfma_f32_16x16x32_bf16 v[120:123], v[148:151], v[178:181], v[120:123]
	v_mfma_f32_16x16x32_bf16 v[116:119], v[140:143], v[208:211], v[116:119]
	v_mfma_f32_16x16x32_bf16 v[112:115], v[148:151], v[208:211], v[112:115]
	v_mfma_f32_16x16x32_bf16 v[108:111], v[140:143], v[228:231], v[108:111]
	v_mfma_f32_16x16x32_bf16 v[104:107], v[148:151], v[228:231], v[104:107]
	v_mfma_f32_16x16x32_bf16 v[100:103], v[140:143], v[236:239], v[100:103]
	v_mfma_f32_16x16x32_bf16 v[96:99], v[148:151], v[236:239], v[96:99]
	v_mfma_f32_16x16x32_bf16 v[124:127], v[144:147], v[182:185], v[124:127]
	v_mfma_f32_16x16x32_bf16 v[120:123], v[158:161], v[182:185], v[120:123]
	v_mfma_f32_16x16x32_bf16 v[116:119], v[144:147], v[212:215], v[116:119]
	v_mfma_f32_16x16x32_bf16 v[112:115], v[158:161], v[212:215], v[112:115]
	v_mfma_f32_16x16x32_bf16 v[108:111], v[144:147], v[232:235], v[108:111]
	v_mfma_f32_16x16x32_bf16 v[104:107], v[158:161], v[232:235], v[104:107]
	v_mfma_f32_16x16x32_bf16 v[100:103], v[144:147], v[240:243], v[100:103]
	v_mfma_f32_16x16x32_bf16 v[96:99], v[158:161], v[240:243], v[96:99]
	s_setprio 0
	s_setprio 1
	v_mfma_f32_16x16x32_bf16 v[60:63], v[162:165], v[178:181], v[60:63]
	v_mfma_f32_16x16x32_bf16 v[56:59], v[170:173], v[178:181], v[56:59]
	v_mfma_f32_16x16x32_bf16 v[52:55], v[162:165], v[208:211], v[52:55]
	v_mfma_f32_16x16x32_bf16 v[48:51], v[170:173], v[208:211], v[48:51]
	v_mfma_f32_16x16x32_bf16 v[44:47], v[162:165], v[228:231], v[44:47]
	v_mfma_f32_16x16x32_bf16 v[40:43], v[170:173], v[228:231], v[40:43]
	v_mfma_f32_16x16x32_bf16 v[36:39], v[162:165], v[236:239], v[36:39]
	v_mfma_f32_16x16x32_bf16 v[32:35], v[170:173], v[236:239], v[32:35]
	v_mfma_f32_16x16x32_bf16 v[60:63], v[166:169], v[182:185], v[60:63]
	v_mfma_f32_16x16x32_bf16 v[56:59], v[174:177], v[182:185], v[56:59]
	v_mfma_f32_16x16x32_bf16 v[52:55], v[166:169], v[212:215], v[52:55]
	v_mfma_f32_16x16x32_bf16 v[48:51], v[174:177], v[212:215], v[48:51]
	v_mfma_f32_16x16x32_bf16 v[44:47], v[166:169], v[232:235], v[44:47]
	v_mfma_f32_16x16x32_bf16 v[40:43], v[174:177], v[232:235], v[40:43]
	v_mfma_f32_16x16x32_bf16 v[36:39], v[166:169], v[240:243], v[36:39]
	v_mfma_f32_16x16x32_bf16 v[32:35], v[174:177], v[240:243], v[32:35]
	s_setprio 0
	s_barrier
	s_add_i32 s10, s10, s3
	v_lshl_add_u64 v[186:187], v[186:187], 0, s[48:49]
	s_mov_b32 m0, s10
	ds_read_b128 v[178:181], v156 offset:49152
	ds_read_b128 v[182:185], v156 offset:50176
	ds_read_b128 v[208:211], v156 offset:51200
	ds_read_b128 v[212:215], v156 offset:52224
	ds_read_b128 v[228:231], v156 offset:53248
	ds_read_b128 v[232:235], v156 offset:54272
	ds_read_b128 v[236:239], v156 offset:55296
	ds_read_b128 v[240:243], v156 offset:56320
	global_load_lds_dwordx4 v[186:187], off
	s_add_i32 m0, s10, 0x2000
	s_add_u32 s46, s46, 0x40080
	v_lshl_add_u64 v[186:187], v[244:245], 0, s[48:49]
	s_addc_u32 s47, s47, 0
	s_add_i32 s10, s33, s3
	global_load_lds_dwordx4 v[186:187], off
	v_lshl_add_u64 v[186:187], s[46:47], 0, v[132:133]
	s_mov_b32 m0, s10
	s_nop 0
	global_load_lds_dwordx4 v[186:187], off
	v_lshl_add_u64 v[186:187], s[46:47], 0, v[128:129]
	s_add_i32 m0, s10, 0x2000
	s_nop 0
	global_load_lds_dwordx4 v[186:187], off
	v_lshl_add_u64 v[186:187], v[246:247], 0, s[48:49]
	s_mov_b32 m0, s71
	s_nop 0
	global_load_lds_dwordx4 v[186:187], off
	v_lshl_add_u64 v[186:187], v[248:249], 0, s[48:49]
	s_mov_b32 m0, s92
	s_nop 0
	global_load_lds_dwordx4 v[186:187], off
	s_waitcnt vmcnt(8)
	s_waitcnt lgkmcnt(0)
	s_barrier
	s_setprio 1
	s_waitcnt lgkmcnt(0)
	v_mfma_f32_16x16x32_bf16 v[92:95], v[140:143], v[178:181], v[92:95]
	v_mfma_f32_16x16x32_bf16 v[88:91], v[148:151], v[178:181], v[88:91]
	v_mfma_f32_16x16x32_bf16 v[84:87], v[140:143], v[208:211], v[84:87]
	v_mfma_f32_16x16x32_bf16 v[80:83], v[148:151], v[208:211], v[80:83]
	v_mfma_f32_16x16x32_bf16 v[76:79], v[140:143], v[228:231], v[76:79]
	v_mfma_f32_16x16x32_bf16 v[72:75], v[148:151], v[228:231], v[72:75]
	v_mfma_f32_16x16x32_bf16 v[68:71], v[140:143], v[236:239], v[68:71]
	v_mfma_f32_16x16x32_bf16 v[64:67], v[148:151], v[236:239], v[64:67]
	v_mfma_f32_16x16x32_bf16 v[92:95], v[144:147], v[182:185], v[92:95]
	v_mfma_f32_16x16x32_bf16 v[88:91], v[158:161], v[182:185], v[88:91]
	v_mfma_f32_16x16x32_bf16 v[84:87], v[144:147], v[212:215], v[84:87]
	v_mfma_f32_16x16x32_bf16 v[80:83], v[158:161], v[212:215], v[80:83]
	v_mfma_f32_16x16x32_bf16 v[76:79], v[144:147], v[232:235], v[76:79]
	v_mfma_f32_16x16x32_bf16 v[72:75], v[158:161], v[232:235], v[72:75]
	v_mfma_f32_16x16x32_bf16 v[68:71], v[144:147], v[240:243], v[68:71]
	v_mfma_f32_16x16x32_bf16 v[64:67], v[158:161], v[240:243], v[64:67]
	s_setprio 0
	s_setprio 1
	v_mfma_f32_16x16x32_bf16 v[28:31], v[162:165], v[178:181], v[28:31]
	v_mfma_f32_16x16x32_bf16 v[24:27], v[170:173], v[178:181], v[24:27]
	v_mfma_f32_16x16x32_bf16 v[20:23], v[162:165], v[208:211], v[20:23]
	v_mfma_f32_16x16x32_bf16 v[16:19], v[170:173], v[208:211], v[16:19]
	v_mfma_f32_16x16x32_bf16 v[12:15], v[162:165], v[228:231], v[12:15]
	v_mfma_f32_16x16x32_bf16 v[8:11], v[170:173], v[228:231], v[8:11]
	v_mfma_f32_16x16x32_bf16 v[4:7], v[162:165], v[236:239], v[4:7]
	v_mfma_f32_16x16x32_bf16 v[0:3], v[170:173], v[236:239], v[0:3]
	v_mfma_f32_16x16x32_bf16 v[28:31], v[166:169], v[182:185], v[28:31]
	v_mfma_f32_16x16x32_bf16 v[24:27], v[174:177], v[182:185], v[24:27]
	v_mfma_f32_16x16x32_bf16 v[20:23], v[166:169], v[212:215], v[20:23]
	v_mfma_f32_16x16x32_bf16 v[16:19], v[174:177], v[212:215], v[16:19]
	v_mfma_f32_16x16x32_bf16 v[12:15], v[166:169], v[232:235], v[12:15]
	v_mfma_f32_16x16x32_bf16 v[8:11], v[174:177], v[232:235], v[8:11]
	v_mfma_f32_16x16x32_bf16 v[4:7], v[166:169], v[240:243], v[4:7]
	v_mfma_f32_16x16x32_bf16 v[0:3], v[174:177], v[240:243], v[0:3]
	s_setprio 0
	s_barrier
	s_add_i32 s73, s73, 2
	s_add_u32 s0, s0, 0x100
	s_addc_u32 s1, s1, 0
	s_add_u32 s60, s60, 0x100
	s_addc_u32 s72, s72, 0
	s_cmp_gt_u32 s73, 13
	s_cbranch_scc0 .LBB0_236
	s_branch .Lgemm1_exit

.Lgemm1_exit:
	s_and_b64 vcc, exec, s[40:41]
	s_cbranch_vccz .LBB0_239
	s_barrier

.LBB0_912:
	s_ashr_i32 s75, s74, 31
	s_lshl_b64 s[34:35], s[74:75], 18
	s_add_u32 s46, s60, s34
	s_addc_u32 s47, s3, s35
	s_and_b64 s[0:1], s[0:1], exec
	s_cselect_b32 s9, s47, s91
	s_cselect_b32 s34, s46, s90
	s_add_u32 s35, s90, 0x100
	s_addc_u32 s41, s91, 0
	s_mov_b32 s45, -2
	s_waitcnt vmcnt(0)
.Lgemm2_peel:
	s_add_u32 s0, s64, 0x100
	s_addc_u32 s1, s65, 0
	s_add_i32 s10, 0, 0x10000
	s_cmp_eq_u32 s45, 4
	s_cselect_b32 vcc_hi, s77, s1
	s_cselect_b32 vcc_lo, s76, s0
	s_cselect_b32 s91, s9, s41
	s_cselect_b32 s90, s34, s35
	s_add_i32 s33, 0, 0x14000
	v_add_u32_e32 v154, s10, v151
	v_add_u32_e32 v170, s33, v151
	ds_read_b128 v[128:131], v154
	ds_read_b128 v[142:145], v154 offset:1024
	ds_read_b128 v[146:149], v154 offset:2048
	ds_read_b128 v[154:157], v154 offset:3072
	ds_read_b128 v[158:161], v170
	ds_read_b128 v[162:165], v170 offset:1024
	ds_read_b128 v[166:169], v170 offset:2048
	ds_read_b128 v[170:173], v170 offset:3072
	v_lshl_add_u64 v[186:187], s[64:65], 0, v[138:139]
	s_add_i32 m0, s12, 0xc000
	ds_read_b128 v[174:177], v153
	ds_read_b128 v[178:181], v153 offset:1024
	ds_read_b128 v[182:185], v153 offset:2048
	ds_read_b128 v[208:211], v153 offset:3072
	ds_read_b128 v[212:215], v153 offset:4096
	ds_read_b128 v[228:231], v153 offset:5120
	ds_read_b128 v[232:235], v153 offset:6144
	ds_read_b128 v[236:239], v153 offset:7168
	global_load_lds_dwordx4 v[186:187], off
	v_lshl_add_u64 v[186:187], s[64:65], 0, v[140:141]
	s_add_i32 m0, s12, 0xe000
	s_nop 0
	global_load_lds_dwordx4 v[186:187], off
	s_waitcnt vmcnt(8)
	s_waitcnt lgkmcnt(0)
	s_barrier
	s_setprio 1
	s_waitcnt lgkmcnt(0)
	v_mfma_f32_16x16x32_bf16 v[124:127], v[128:131], v[174:177], 0
	v_mfma_f32_16x16x32_bf16 v[120:123], v[146:149], v[174:177], 0
	v_mfma_f32_16x16x32_bf16 v[108:111], v[128:131], v[182:185], 0
	v_mfma_f32_16x16x32_bf16 v[104:107], v[146:149], v[182:185], 0
	v_mfma_f32_16x16x32_bf16 v[92:95], v[128:131], v[212:215], 0
	v_mfma_f32_16x16x32_bf16 v[88:91], v[146:149], v[212:215], 0
	v_mfma_f32_16x16x32_bf16 v[76:79], v[128:131], v[232:235], 0
	v_mfma_f32_16x16x32_bf16 v[72:75], v[146:149], v[232:235], 0
	v_mfma_f32_16x16x32_bf16 v[124:127], v[142:145], v[178:181], v[124:127]
	v_mfma_f32_16x16x32_bf16 v[120:123], v[154:157], v[178:181], v[120:123]
	v_mfma_f32_16x16x32_bf16 v[108:111], v[142:145], v[208:211], v[108:111]
	v_mfma_f32_16x16x32_bf16 v[104:107], v[154:157], v[208:211], v[104:107]
	v_mfma_f32_16x16x32_bf16 v[92:95], v[142:145], v[228:231], v[92:95]
	v_mfma_f32_16x16x32_bf16 v[88:91], v[154:157], v[228:231], v[88:91]
	v_mfma_f32_16x16x32_bf16 v[76:79], v[142:145], v[236:239], v[76:79]
	v_mfma_f32_16x16x32_bf16 v[72:75], v[154:157], v[236:239], v[72:75]
	s_setprio 0
	s_setprio 1
	v_mfma_f32_16x16x32_bf16 v[116:119], v[158:161], v[174:177], 0
	v_mfma_f32_16x16x32_bf16 v[112:115], v[166:169], v[174:177], 0
	v_mfma_f32_16x16x32_bf16 v[100:103], v[158:161], v[182:185], 0
	v_mfma_f32_16x16x32_bf16 v[96:99], v[166:169], v[182:185], 0
	v_mfma_f32_16x16x32_bf16 v[84:87], v[158:161], v[212:215], 0
	v_mfma_f32_16x16x32_bf16 v[80:83], v[166:169], v[212:215], 0
	v_mfma_f32_16x16x32_bf16 v[68:71], v[158:161], v[232:235], 0
	v_mfma_f32_16x16x32_bf16 v[64:67], v[166:169], v[232:235], 0
	v_mfma_f32_16x16x32_bf16 v[116:119], v[162:165], v[178:181], v[116:119]
	v_mfma_f32_16x16x32_bf16 v[112:115], v[170:173], v[178:181], v[112:115]
	v_mfma_f32_16x16x32_bf16 v[100:103], v[162:165], v[208:211], v[100:103]
	v_mfma_f32_16x16x32_bf16 v[96:99], v[170:173], v[208:211], v[96:99]
	v_mfma_f32_16x16x32_bf16 v[84:87], v[162:165], v[228:231], v[84:87]
	v_mfma_f32_16x16x32_bf16 v[80:83], v[170:173], v[228:231], v[80:83]
	v_mfma_f32_16x16x32_bf16 v[68:71], v[162:165], v[236:239], v[68:71]
	v_mfma_f32_16x16x32_bf16 v[64:67], v[170:173], v[236:239], v[64:67]
	s_setprio 0
	s_barrier
	s_add_i32 s10, s10, s11
	v_lshl_add_u64 v[186:187], s[90:91], 0, v[194:195]
	s_mov_b32 m0, s10
	ds_read_b128 v[174:177], v153 offset:16384
	ds_read_b128 v[178:181], v153 offset:17408
	ds_read_b128 v[182:185], v153 offset:18432
	ds_read_b128 v[208:211], v153 offset:19456
	ds_read_b128 v[212:215], v153 offset:20480
	ds_read_b128 v[228:231], v153 offset:21504
	ds_read_b128 v[232:235], v153 offset:22528
	ds_read_b128 v[236:239], v153 offset:23552
	global_load_lds_dwordx4 v[186:187], off
	s_add_i32 m0, s10, 0x2000
	s_add_u32 s64, s90, 0x20000
	v_lshl_add_u64 v[240:241], s[90:91], 0, v[132:133]
	s_addc_u32 s65, s91, 0
	s_add_i32 s10, s33, s11
	global_load_lds_dwordx4 v[240:241], off
	v_lshl_add_u64 v[242:243], s[64:65], 0, v[194:195]
	s_mov_b32 m0, s10
	v_lshl_add_u64 v[244:245], vcc, 0, v[134:135]
	global_load_lds_dwordx4 v[242:243], off
	v_lshl_add_u64 v[242:243], s[64:65], 0, v[132:133]
	s_add_i32 m0, s10, 0x2000
	s_nop 0
	global_load_lds_dwordx4 v[242:243], off
	v_lshl_add_u64 v[242:243], vcc, 0, v[136:137]
	s_mov_b32 m0, s12
	s_nop 0
	global_load_lds_dwordx4 v[242:243], off
	s_mov_b32 m0, s16
	s_nop 0
	global_load_lds_dwordx4 v[244:245], off
	s_waitcnt vmcnt(8)
	s_waitcnt lgkmcnt(0)
	s_barrier
	s_setprio 1
	s_waitcnt lgkmcnt(0)
	v_mfma_f32_16x16x32_bf16 v[60:63], v[128:131], v[174:177], 0
	v_mfma_f32_16x16x32_bf16 v[56:59], v[146:149], v[174:177], 0
	v_mfma_f32_16x16x32_bf16 v[44:47], v[128:131], v[182:185], 0
	v_mfma_f32_16x16x32_bf16 v[40:43], v[146:149], v[182:185], 0
	v_mfma_f32_16x16x32_bf16 v[28:31], v[128:131], v[212:215], 0
	v_mfma_f32_16x16x32_bf16 v[24:27], v[146:149], v[212:215], 0
	v_mfma_f32_16x16x32_bf16 v[12:15], v[128:131], v[232:235], 0
	v_mfma_f32_16x16x32_bf16 v[8:11], v[146:149], v[232:235], 0
	v_mfma_f32_16x16x32_bf16 v[60:63], v[142:145], v[178:181], v[60:63]
	v_mfma_f32_16x16x32_bf16 v[56:59], v[154:157], v[178:181], v[56:59]
	v_mfma_f32_16x16x32_bf16 v[44:47], v[142:145], v[208:211], v[44:47]
	v_mfma_f32_16x16x32_bf16 v[40:43], v[154:157], v[208:211], v[40:43]
	v_mfma_f32_16x16x32_bf16 v[28:31], v[142:145], v[228:231], v[28:31]
	v_mfma_f32_16x16x32_bf16 v[24:27], v[154:157], v[228:231], v[24:27]
	v_mfma_f32_16x16x32_bf16 v[12:15], v[142:145], v[236:239], v[12:15]
	v_mfma_f32_16x16x32_bf16 v[8:11], v[154:157], v[236:239], v[8:11]
	s_setprio 0
	s_setprio 1
	v_mfma_f32_16x16x32_bf16 v[52:55], v[158:161], v[174:177], 0
	v_mfma_f32_16x16x32_bf16 v[48:51], v[166:169], v[174:177], 0
	v_mfma_f32_16x16x32_bf16 v[36:39], v[158:161], v[182:185], 0
	v_mfma_f32_16x16x32_bf16 v[32:35], v[166:169], v[182:185], 0
	v_mfma_f32_16x16x32_bf16 v[20:23], v[158:161], v[212:215], 0
	v_mfma_f32_16x16x32_bf16 v[16:19], v[166:169], v[212:215], 0
	v_mfma_f32_16x16x32_bf16 v[4:7], v[158:161], v[232:235], 0
	v_mfma_f32_16x16x32_bf16 v[0:3], v[166:169], v[232:235], 0
	v_mfma_f32_16x16x32_bf16 v[52:55], v[162:165], v[178:181], v[52:55]
	v_mfma_f32_16x16x32_bf16 v[48:51], v[170:173], v[178:181], v[48:51]
	v_mfma_f32_16x16x32_bf16 v[36:39], v[162:165], v[208:211], v[36:39]
	v_mfma_f32_16x16x32_bf16 v[32:35], v[170:173], v[208:211], v[32:35]
	v_mfma_f32_16x16x32_bf16 v[20:23], v[162:165], v[228:231], v[20:23]
	v_mfma_f32_16x16x32_bf16 v[16:19], v[170:173], v[228:231], v[16:19]
	v_mfma_f32_16x16x32_bf16 v[4:7], v[162:165], v[236:239], v[4:7]
	v_mfma_f32_16x16x32_bf16 v[0:3], v[170:173], v[236:239], v[0:3]
	s_setprio 0
	s_barrier
	s_add_i32 s10, 0, 0x18000
	s_add_i32 s33, 0, 0x1c000
	v_add_u32_e32 v154, s10, v151
	v_add_u32_e32 v170, s33, v151
	ds_read_b128 v[128:131], v154
	ds_read_b128 v[142:145], v154 offset:1024
	ds_read_b128 v[146:149], v154 offset:2048
	ds_read_b128 v[154:157], v154 offset:3072
	ds_read_b128 v[158:161], v170
	ds_read_b128 v[162:165], v170 offset:1024
	ds_read_b128 v[166:169], v170 offset:2048
	ds_read_b128 v[170:173], v170 offset:3072
	s_add_u32 s64, vcc_lo, 0x160000
	s_addc_u32 s65, vcc_hi, 0
	s_mov_b32 m0, s17
	v_lshl_add_u64 v[246:247], s[64:65], 0, v[136:137]
	ds_read_b128 v[174:177], v153 offset:32768
	ds_read_b128 v[178:181], v153 offset:33792
	ds_read_b128 v[182:185], v153 offset:34816
	ds_read_b128 v[208:211], v153 offset:35840
	ds_read_b128 v[212:215], v153 offset:36864
	ds_read_b128 v[228:231], v153 offset:37888
	ds_read_b128 v[232:235], v153 offset:38912
	ds_read_b128 v[236:239], v153 offset:39936
	global_load_lds_dwordx4 v[246:247], off
	v_lshl_add_u64 v[246:247], s[64:65], 0, v[134:135]
	s_mov_b32 m0, s18
	s_nop 0
	global_load_lds_dwordx4 v[246:247], off
	s_waitcnt vmcnt(8)
	s_waitcnt lgkmcnt(0)
	s_barrier
	s_setprio 1
	s_waitcnt lgkmcnt(0)
	v_mfma_f32_16x16x32_bf16 v[124:127], v[128:131], v[174:177], v[124:127]
	v_mfma_f32_16x16x32_bf16 v[120:123], v[146:149], v[174:177], v[120:123]
	v_mfma_f32_16x16x32_bf16 v[108:111], v[128:131], v[182:185], v[108:111]
	v_mfma_f32_16x16x32_bf16 v[104:107], v[146:149], v[182:185], v[104:107]
	v_mfma_f32_16x16x32_bf16 v[92:95], v[128:131], v[212:215], v[92:95]
	v_mfma_f32_16x16x32_bf16 v[88:91], v[146:149], v[212:215], v[88:91]
	v_mfma_f32_16x16x32_bf16 v[76:79], v[128:131], v[232:235], v[76:79]
	v_mfma_f32_16x16x32_bf16 v[72:75], v[146:149], v[232:235], v[72:75]
	v_mfma_f32_16x16x32_bf16 v[124:127], v[142:145], v[178:181], v[124:127]
	v_mfma_f32_16x16x32_bf16 v[120:123], v[154:157], v[178:181], v[120:123]
	v_mfma_f32_16x16x32_bf16 v[108:111], v[142:145], v[208:211], v[108:111]
	v_mfma_f32_16x16x32_bf16 v[104:107], v[154:157], v[208:211], v[104:107]
	v_mfma_f32_16x16x32_bf16 v[92:95], v[142:145], v[228:231], v[92:95]
	v_mfma_f32_16x16x32_bf16 v[88:91], v[154:157], v[228:231], v[88:91]
	v_mfma_f32_16x16x32_bf16 v[76:79], v[142:145], v[236:239], v[76:79]
	v_mfma_f32_16x16x32_bf16 v[72:75], v[154:157], v[236:239], v[72:75]
	s_setprio 0
	s_setprio 1
	v_mfma_f32_16x16x32_bf16 v[116:119], v[158:161], v[174:177], v[116:119]
	v_mfma_f32_16x16x32_bf16 v[112:115], v[166:169], v[174:177], v[112:115]
	v_mfma_f32_16x16x32_bf16 v[100:103], v[158:161], v[182:185], v[100:103]
	v_mfma_f32_16x16x32_bf16 v[96:99], v[166:169], v[182:185], v[96:99]
	v_mfma_f32_16x16x32_bf16 v[84:87], v[158:161], v[212:215], v[84:87]
	v_mfma_f32_16x16x32_bf16 v[80:83], v[166:169], v[212:215], v[80:83]
	v_mfma_f32_16x16x32_bf16 v[68:71], v[158:161], v[232:235], v[68:71]
	v_mfma_f32_16x16x32_bf16 v[64:67], v[166:169], v[232:235], v[64:67]
	v_mfma_f32_16x16x32_bf16 v[116:119], v[162:165], v[178:181], v[116:119]
	v_mfma_f32_16x16x32_bf16 v[112:115], v[170:173], v[178:181], v[112:115]
	v_mfma_f32_16x16x32_bf16 v[100:103], v[162:165], v[208:211], v[100:103]
	v_mfma_f32_16x16x32_bf16 v[96:99], v[170:173], v[208:211], v[96:99]
	v_mfma_f32_16x16x32_bf16 v[84:87], v[162:165], v[228:231], v[84:87]
	v_mfma_f32_16x16x32_bf16 v[80:83], v[170:173], v[228:231], v[80:83]
	v_mfma_f32_16x16x32_bf16 v[68:71], v[162:165], v[236:239], v[68:71]
	v_mfma_f32_16x16x32_bf16 v[64:67], v[170:173], v[236:239], v[64:67]
	s_setprio 0
	s_barrier
	s_add_i32 s10, s10, s11
	v_lshl_add_u64 v[186:187], v[186:187], 0, s[48:49]
	s_mov_b32 m0, s10
	ds_read_b128 v[174:177], v153 offset:49152
	ds_read_b128 v[178:181], v153 offset:50176
	ds_read_b128 v[182:185], v153 offset:51200
	ds_read_b128 v[208:211], v153 offset:52224
	ds_read_b128 v[212:215], v153 offset:53248
	ds_read_b128 v[228:231], v153 offset:54272
	ds_read_b128 v[232:235], v153 offset:55296
	ds_read_b128 v[236:239], v153 offset:56320
	global_load_lds_dwordx4 v[186:187], off
	s_add_i32 m0, s10, 0x2000
	s_add_u32 s64, s90, 0x20080
	v_lshl_add_u64 v[186:187], v[240:241], 0, s[48:49]
	s_addc_u32 s65, s91, 0
	s_add_i32 s10, s33, s11
	global_load_lds_dwordx4 v[186:187], off
	v_lshl_add_u64 v[186:187], s[64:65], 0, v[194:195]
	s_mov_b32 m0, s10
	s_nop 0
	global_load_lds_dwordx4 v[186:187], off
	v_lshl_add_u64 v[186:187], s[64:65], 0, v[132:133]
	s_add_i32 m0, s10, 0x2000
	s_nop 0
	global_load_lds_dwordx4 v[186:187], off
	v_lshl_add_u64 v[186:187], v[242:243], 0, s[48:49]
	s_mov_b32 m0, s92
	s_nop 0
	global_load_lds_dwordx4 v[186:187], off
	v_lshl_add_u64 v[186:187], v[244:245], 0, s[48:49]
	s_mov_b32 m0, s94
	s_nop 0
	global_load_lds_dwordx4 v[186:187], off
	s_waitcnt vmcnt(8)
	s_waitcnt lgkmcnt(0)
	s_barrier
	s_setprio 1
	s_waitcnt lgkmcnt(0)
	v_mfma_f32_16x16x32_bf16 v[60:63], v[128:131], v[174:177], v[60:63]
	v_mfma_f32_16x16x32_bf16 v[56:59], v[146:149], v[174:177], v[56:59]
	v_mfma_f32_16x16x32_bf16 v[44:47], v[128:131], v[182:185], v[44:47]
	v_mfma_f32_16x16x32_bf16 v[40:43], v[146:149], v[182:185], v[40:43]
	v_mfma_f32_16x16x32_bf16 v[28:31], v[128:131], v[212:215], v[28:31]
	v_mfma_f32_16x16x32_bf16 v[24:27], v[146:149], v[212:215], v[24:27]
	v_mfma_f32_16x16x32_bf16 v[12:15], v[128:131], v[232:235], v[12:15]
	v_mfma_f32_16x16x32_bf16 v[8:11], v[146:149], v[232:235], v[8:11]
	v_mfma_f32_16x16x32_bf16 v[60:63], v[142:145], v[178:181], v[60:63]
	v_mfma_f32_16x16x32_bf16 v[56:59], v[154:157], v[178:181], v[56:59]
	v_mfma_f32_16x16x32_bf16 v[44:47], v[142:145], v[208:211], v[44:47]
	v_mfma_f32_16x16x32_bf16 v[40:43], v[154:157], v[208:211], v[40:43]
	v_mfma_f32_16x16x32_bf16 v[28:31], v[142:145], v[228:231], v[28:31]
	v_mfma_f32_16x16x32_bf16 v[24:27], v[154:157], v[228:231], v[24:27]
	v_mfma_f32_16x16x32_bf16 v[12:15], v[142:145], v[236:239], v[12:15]
	v_mfma_f32_16x16x32_bf16 v[8:11], v[154:157], v[236:239], v[8:11]
	s_setprio 0
	s_setprio 1
	v_mfma_f32_16x16x32_bf16 v[52:55], v[158:161], v[174:177], v[52:55]
	v_mfma_f32_16x16x32_bf16 v[48:51], v[166:169], v[174:177], v[48:51]
	v_mfma_f32_16x16x32_bf16 v[36:39], v[158:161], v[182:185], v[36:39]
	v_mfma_f32_16x16x32_bf16 v[32:35], v[166:169], v[182:185], v[32:35]
	v_mfma_f32_16x16x32_bf16 v[20:23], v[158:161], v[212:215], v[20:23]
	v_mfma_f32_16x16x32_bf16 v[16:19], v[166:169], v[212:215], v[16:19]
	v_mfma_f32_16x16x32_bf16 v[4:7], v[158:161], v[232:235], v[4:7]
	v_mfma_f32_16x16x32_bf16 v[0:3], v[166:169], v[232:235], v[0:3]
	v_mfma_f32_16x16x32_bf16 v[52:55], v[162:165], v[178:181], v[52:55]
	v_mfma_f32_16x16x32_bf16 v[48:51], v[170:173], v[178:181], v[48:51]
	v_mfma_f32_16x16x32_bf16 v[36:39], v[162:165], v[208:211], v[36:39]
	v_mfma_f32_16x16x32_bf16 v[32:35], v[170:173], v[208:211], v[32:35]
	v_mfma_f32_16x16x32_bf16 v[20:23], v[162:165], v[228:231], v[20:23]
	v_mfma_f32_16x16x32_bf16 v[16:19], v[170:173], v[228:231], v[16:19]
	v_mfma_f32_16x16x32_bf16 v[4:7], v[162:165], v[236:239], v[4:7]
	v_mfma_f32_16x16x32_bf16 v[0:3], v[170:173], v[236:239], v[0:3]
	s_setprio 0
	s_barrier
	s_add_i32 s45, s45, 2
	s_add_u32 s35, s35, 0x100
	s_addc_u32 s41, s41, 0
	s_cmp_gt_u32 s45, 5
	s_mov_b64 s[64:65], s[0:1]
	s_cbranch_scc0 .LBB0_913
	s_branch .Lgemm2_exit

.Lgemm2_exit:
	s_and_b64 vcc, exec, s[36:37]
	s_cbranch_vccz .LBB0_916
	s_barrier

.LBB0_1019:
	s_ashr_i32 s73, s72, 31
	s_lshl_b64 s[34:35], s[72:73], 20
	s_add_u32 s76, s67, s34
	s_addc_u32 s77, s69, s35
	s_and_b64 s[0:1], s[0:1], exec
	s_cselect_b32 s9, s77, s47
	s_cselect_b32 s34, s76, s46
	s_add_u32 s35, s46, 0x100
	s_addc_u32 s73, s47, 0
	s_mov_b32 s78, -2
	s_waitcnt lgkmcnt(0)
	s_waitcnt vmcnt(0)
.Lgemm3_peel:
	s_add_u32 s0, s90, 0x100
	s_addc_u32 s1, s91, 0
	s_add_i32 s10, 0, 0x10000
	s_cmp_eq_u32 s78, 28
	s_cselect_b32 vcc_hi, s75, s1
	s_cselect_b32 vcc_lo, s74, s0
	s_cselect_b32 s47, s9, s73
	s_cselect_b32 s46, s34, s35
	s_add_i32 s33, 0, 0x14000
	v_add_u32_e32 v154, s10, v144
	v_add_u32_e32 v170, s33, v144
	ds_read_b128 v[140:143], v154
	ds_read_b128 v[146:149], v154 offset:1024
	ds_read_b128 v[150:153], v154 offset:2048
	ds_read_b128 v[154:157], v154 offset:3072
	ds_read_b128 v[158:161], v170
	ds_read_b128 v[162:165], v170 offset:1024
	ds_read_b128 v[166:169], v170 offset:2048
	ds_read_b128 v[170:173], v170 offset:3072
	v_lshl_add_u64 v[186:187], s[90:91], 0, v[136:137]
	s_add_i32 m0, s11, 0xc000
	ds_read_b128 v[174:177], v145
	ds_read_b128 v[178:181], v145 offset:1024
	ds_read_b128 v[182:185], v145 offset:2048
	ds_read_b128 v[208:211], v145 offset:3072
	ds_read_b128 v[212:215], v145 offset:4096
	ds_read_b128 v[228:231], v145 offset:5120
	ds_read_b128 v[232:235], v145 offset:6144
	ds_read_b128 v[236:239], v145 offset:7168
	global_load_lds_dwordx4 v[186:187], off
	v_lshl_add_u64 v[186:187], s[90:91], 0, v[138:139]
	s_add_i32 m0, s11, 0xe000
	s_nop 0
	global_load_lds_dwordx4 v[186:187], off
	s_waitcnt vmcnt(8)
	s_waitcnt lgkmcnt(0)
	s_barrier
	s_setprio 1
	s_waitcnt lgkmcnt(0)
	v_mfma_f32_16x16x32_bf16 v[124:127], v[140:143], v[174:177], 0
	v_mfma_f32_16x16x32_bf16 v[120:123], v[150:153], v[174:177], 0
	v_mfma_f32_16x16x32_bf16 v[108:111], v[140:143], v[182:185], 0
	v_mfma_f32_16x16x32_bf16 v[104:107], v[150:153], v[182:185], 0
	v_mfma_f32_16x16x32_bf16 v[92:95], v[140:143], v[212:215], 0
	v_mfma_f32_16x16x32_bf16 v[88:91], v[150:153], v[212:215], 0
	v_mfma_f32_16x16x32_bf16 v[76:79], v[140:143], v[232:235], 0
	v_mfma_f32_16x16x32_bf16 v[72:75], v[150:153], v[232:235], 0
	v_mfma_f32_16x16x32_bf16 v[124:127], v[146:149], v[178:181], v[124:127]
	v_mfma_f32_16x16x32_bf16 v[120:123], v[154:157], v[178:181], v[120:123]
	v_mfma_f32_16x16x32_bf16 v[108:111], v[146:149], v[208:211], v[108:111]
	v_mfma_f32_16x16x32_bf16 v[104:107], v[154:157], v[208:211], v[104:107]
	v_mfma_f32_16x16x32_bf16 v[92:95], v[146:149], v[228:231], v[92:95]
	v_mfma_f32_16x16x32_bf16 v[88:91], v[154:157], v[228:231], v[88:91]
	v_mfma_f32_16x16x32_bf16 v[76:79], v[146:149], v[236:239], v[76:79]
	v_mfma_f32_16x16x32_bf16 v[72:75], v[154:157], v[236:239], v[72:75]
	s_setprio 0
	s_setprio 1
	v_mfma_f32_16x16x32_bf16 v[116:119], v[158:161], v[174:177], 0
	v_mfma_f32_16x16x32_bf16 v[112:115], v[166:169], v[174:177], 0
	v_mfma_f32_16x16x32_bf16 v[100:103], v[158:161], v[182:185], 0
	v_mfma_f32_16x16x32_bf16 v[96:99], v[166:169], v[182:185], 0
	v_mfma_f32_16x16x32_bf16 v[84:87], v[158:161], v[212:215], 0
	v_mfma_f32_16x16x32_bf16 v[80:83], v[166:169], v[212:215], 0
	v_mfma_f32_16x16x32_bf16 v[68:71], v[158:161], v[232:235], 0
	v_mfma_f32_16x16x32_bf16 v[64:67], v[166:169], v[232:235], 0
	v_mfma_f32_16x16x32_bf16 v[116:119], v[162:165], v[178:181], v[116:119]
	v_mfma_f32_16x16x32_bf16 v[112:115], v[170:173], v[178:181], v[112:115]
	v_mfma_f32_16x16x32_bf16 v[100:103], v[162:165], v[208:211], v[100:103]
	v_mfma_f32_16x16x32_bf16 v[96:99], v[170:173], v[208:211], v[96:99]
	v_mfma_f32_16x16x32_bf16 v[84:87], v[162:165], v[228:231], v[84:87]
	v_mfma_f32_16x16x32_bf16 v[80:83], v[170:173], v[228:231], v[80:83]
	v_mfma_f32_16x16x32_bf16 v[68:71], v[162:165], v[236:239], v[68:71]
	v_mfma_f32_16x16x32_bf16 v[64:67], v[170:173], v[236:239], v[64:67]
	s_setprio 0
	s_barrier
	s_add_i32 s10, s10, s3
	v_lshl_add_u64 v[186:187], s[46:47], 0, v[194:195]
	s_mov_b32 m0, s10
	ds_read_b128 v[174:177], v145 offset:16384
	ds_read_b128 v[178:181], v145 offset:17408
	ds_read_b128 v[182:185], v145 offset:18432
	ds_read_b128 v[208:211], v145 offset:19456
	ds_read_b128 v[212:215], v145 offset:20480
	ds_read_b128 v[228:231], v145 offset:21504
	ds_read_b128 v[232:235], v145 offset:22528
	ds_read_b128 v[236:239], v145 offset:23552
	global_load_lds_dwordx4 v[186:187], off
	s_add_i32 m0, s10, 0x2000
	s_add_u32 s90, s46, 0x80000
	v_lshl_add_u64 v[240:241], s[46:47], 0, v[128:129]
	s_addc_u32 s91, s47, 0
	s_add_i32 s10, s33, s3
	global_load_lds_dwordx4 v[240:241], off
	v_lshl_add_u64 v[242:243], s[90:91], 0, v[194:195]
	s_mov_b32 m0, s10
	v_lshl_add_u64 v[244:245], vcc, 0, v[130:131]
	global_load_lds_dwordx4 v[242:243], off
	v_lshl_add_u64 v[242:243], s[90:91], 0, v[128:129]
	s_add_i32 m0, s10, 0x2000
	s_nop 0
	global_load_lds_dwordx4 v[242:243], off
	v_lshl_add_u64 v[242:243], vcc, 0, v[132:133]
	s_mov_b32 m0, s11
	s_nop 0
	global_load_lds_dwordx4 v[242:243], off
	s_mov_b32 m0, s12
	s_nop 0
	global_load_lds_dwordx4 v[244:245], off
	s_waitcnt vmcnt(8)
	s_waitcnt lgkmcnt(0)
	s_barrier
	s_setprio 1
	s_waitcnt lgkmcnt(0)
	v_mfma_f32_16x16x32_bf16 v[60:63], v[140:143], v[174:177], 0
	v_mfma_f32_16x16x32_bf16 v[56:59], v[150:153], v[174:177], 0
	v_mfma_f32_16x16x32_bf16 v[44:47], v[140:143], v[182:185], 0
	v_mfma_f32_16x16x32_bf16 v[40:43], v[150:153], v[182:185], 0
	v_mfma_f32_16x16x32_bf16 v[28:31], v[140:143], v[212:215], 0
	v_mfma_f32_16x16x32_bf16 v[24:27], v[150:153], v[212:215], 0
	v_mfma_f32_16x16x32_bf16 v[12:15], v[140:143], v[232:235], 0
	v_mfma_f32_16x16x32_bf16 v[8:11], v[150:153], v[232:235], 0
	v_mfma_f32_16x16x32_bf16 v[60:63], v[146:149], v[178:181], v[60:63]
	v_mfma_f32_16x16x32_bf16 v[56:59], v[154:157], v[178:181], v[56:59]
	v_mfma_f32_16x16x32_bf16 v[44:47], v[146:149], v[208:211], v[44:47]
	v_mfma_f32_16x16x32_bf16 v[40:43], v[154:157], v[208:211], v[40:43]
	v_mfma_f32_16x16x32_bf16 v[28:31], v[146:149], v[228:231], v[28:31]
	v_mfma_f32_16x16x32_bf16 v[24:27], v[154:157], v[228:231], v[24:27]
	v_mfma_f32_16x16x32_bf16 v[12:15], v[146:149], v[236:239], v[12:15]
	v_mfma_f32_16x16x32_bf16 v[8:11], v[154:157], v[236:239], v[8:11]
	s_setprio 0
	s_setprio 1
	v_mfma_f32_16x16x32_bf16 v[52:55], v[158:161], v[174:177], 0
	v_mfma_f32_16x16x32_bf16 v[48:51], v[166:169], v[174:177], 0
	v_mfma_f32_16x16x32_bf16 v[36:39], v[158:161], v[182:185], 0
	v_mfma_f32_16x16x32_bf16 v[32:35], v[166:169], v[182:185], 0
	v_mfma_f32_16x16x32_bf16 v[20:23], v[158:161], v[212:215], 0
	v_mfma_f32_16x16x32_bf16 v[16:19], v[166:169], v[212:215], 0
	v_mfma_f32_16x16x32_bf16 v[4:7], v[158:161], v[232:235], 0
	v_mfma_f32_16x16x32_bf16 v[0:3], v[166:169], v[232:235], 0
	v_mfma_f32_16x16x32_bf16 v[52:55], v[162:165], v[178:181], v[52:55]
	v_mfma_f32_16x16x32_bf16 v[48:51], v[170:173], v[178:181], v[48:51]
	v_mfma_f32_16x16x32_bf16 v[36:39], v[162:165], v[208:211], v[36:39]
	v_mfma_f32_16x16x32_bf16 v[32:35], v[170:173], v[208:211], v[32:35]
	v_mfma_f32_16x16x32_bf16 v[20:23], v[162:165], v[228:231], v[20:23]
	v_mfma_f32_16x16x32_bf16 v[16:19], v[170:173], v[228:231], v[16:19]
	v_mfma_f32_16x16x32_bf16 v[4:7], v[162:165], v[236:239], v[4:7]
	v_mfma_f32_16x16x32_bf16 v[0:3], v[170:173], v[236:239], v[0:3]
	s_setprio 0
	s_barrier
	s_add_i32 s10, 0, 0x18000
	s_add_i32 s33, 0, 0x1c000
	v_add_u32_e32 v154, s10, v144
	v_add_u32_e32 v170, s33, v144
	ds_read_b128 v[140:143], v154
	ds_read_b128 v[146:149], v154 offset:1024
	ds_read_b128 v[150:153], v154 offset:2048
	ds_read_b128 v[154:157], v154 offset:3072
	ds_read_b128 v[158:161], v170
	ds_read_b128 v[162:165], v170 offset:1024
	ds_read_b128 v[166:169], v170 offset:2048
	ds_read_b128 v[170:173], v170 offset:3072
	s_add_u32 s90, vcc_lo, 0x160000
	s_addc_u32 s91, vcc_hi, 0
	s_mov_b32 m0, s16
	v_lshl_add_u64 v[246:247], s[90:91], 0, v[132:133]
	ds_read_b128 v[174:177], v145 offset:32768
	ds_read_b128 v[178:181], v145 offset:33792
	ds_read_b128 v[182:185], v145 offset:34816
	ds_read_b128 v[208:211], v145 offset:35840
	ds_read_b128 v[212:215], v145 offset:36864
	ds_read_b128 v[228:231], v145 offset:37888
	ds_read_b128 v[232:235], v145 offset:38912
	ds_read_b128 v[236:239], v145 offset:39936
	global_load_lds_dwordx4 v[246:247], off
	v_lshl_add_u64 v[246:247], s[90:91], 0, v[130:131]
	s_mov_b32 m0, s17
	s_nop 0
	global_load_lds_dwordx4 v[246:247], off
	s_waitcnt vmcnt(8)
	s_waitcnt lgkmcnt(0)
	s_barrier
	s_setprio 1
	s_waitcnt lgkmcnt(0)
	v_mfma_f32_16x16x32_bf16 v[124:127], v[140:143], v[174:177], v[124:127]
	v_mfma_f32_16x16x32_bf16 v[120:123], v[150:153], v[174:177], v[120:123]
	v_mfma_f32_16x16x32_bf16 v[108:111], v[140:143], v[182:185], v[108:111]
	v_mfma_f32_16x16x32_bf16 v[104:107], v[150:153], v[182:185], v[104:107]
	v_mfma_f32_16x16x32_bf16 v[92:95], v[140:143], v[212:215], v[92:95]
	v_mfma_f32_16x16x32_bf16 v[88:91], v[150:153], v[212:215], v[88:91]
	v_mfma_f32_16x16x32_bf16 v[76:79], v[140:143], v[232:235], v[76:79]
	v_mfma_f32_16x16x32_bf16 v[72:75], v[150:153], v[232:235], v[72:75]
	v_mfma_f32_16x16x32_bf16 v[124:127], v[146:149], v[178:181], v[124:127]
	v_mfma_f32_16x16x32_bf16 v[120:123], v[154:157], v[178:181], v[120:123]
	v_mfma_f32_16x16x32_bf16 v[108:111], v[146:149], v[208:211], v[108:111]
	v_mfma_f32_16x16x32_bf16 v[104:107], v[154:157], v[208:211], v[104:107]
	v_mfma_f32_16x16x32_bf16 v[92:95], v[146:149], v[228:231], v[92:95]
	v_mfma_f32_16x16x32_bf16 v[88:91], v[154:157], v[228:231], v[88:91]
	v_mfma_f32_16x16x32_bf16 v[76:79], v[146:149], v[236:239], v[76:79]
	v_mfma_f32_16x16x32_bf16 v[72:75], v[154:157], v[236:239], v[72:75]
	s_setprio 0
	s_setprio 1
	v_mfma_f32_16x16x32_bf16 v[116:119], v[158:161], v[174:177], v[116:119]
	v_mfma_f32_16x16x32_bf16 v[112:115], v[166:169], v[174:177], v[112:115]
	v_mfma_f32_16x16x32_bf16 v[100:103], v[158:161], v[182:185], v[100:103]
	v_mfma_f32_16x16x32_bf16 v[96:99], v[166:169], v[182:185], v[96:99]
	v_mfma_f32_16x16x32_bf16 v[84:87], v[158:161], v[212:215], v[84:87]
	v_mfma_f32_16x16x32_bf16 v[80:83], v[166:169], v[212:215], v[80:83]
	v_mfma_f32_16x16x32_bf16 v[68:71], v[158:161], v[232:235], v[68:71]
	v_mfma_f32_16x16x32_bf16 v[64:67], v[166:169], v[232:235], v[64:67]
	v_mfma_f32_16x16x32_bf16 v[116:119], v[162:165], v[178:181], v[116:119]
	v_mfma_f32_16x16x32_bf16 v[112:115], v[170:173], v[178:181], v[112:115]
	v_mfma_f32_16x16x32_bf16 v[100:103], v[162:165], v[208:211], v[100:103]
	v_mfma_f32_16x16x32_bf16 v[96:99], v[170:173], v[208:211], v[96:99]
	v_mfma_f32_16x16x32_bf16 v[84:87], v[162:165], v[228:231], v[84:87]
	v_mfma_f32_16x16x32_bf16 v[80:83], v[170:173], v[228:231], v[80:83]
	v_mfma_f32_16x16x32_bf16 v[68:71], v[162:165], v[236:239], v[68:71]
	v_mfma_f32_16x16x32_bf16 v[64:67], v[170:173], v[236:239], v[64:67]
	s_setprio 0
	s_barrier
	s_add_i32 s10, s10, s3
	v_lshl_add_u64 v[186:187], v[186:187], 0, s[48:49]
	s_mov_b32 m0, s10
	ds_read_b128 v[174:177], v145 offset:49152
	ds_read_b128 v[178:181], v145 offset:50176
	ds_read_b128 v[182:185], v145 offset:51200
	ds_read_b128 v[208:211], v145 offset:52224
	ds_read_b128 v[212:215], v145 offset:53248
	ds_read_b128 v[228:231], v145 offset:54272
	ds_read_b128 v[232:235], v145 offset:55296
	ds_read_b128 v[236:239], v145 offset:56320
	global_load_lds_dwordx4 v[186:187], off
	s_add_i32 m0, s10, 0x2000
	s_add_u32 s46, s46, 0x80080
	v_lshl_add_u64 v[186:187], v[240:241], 0, s[48:49]
	s_addc_u32 s47, s47, 0
	s_add_i32 s10, s33, s3
	global_load_lds_dwordx4 v[186:187], off
	v_lshl_add_u64 v[186:187], s[46:47], 0, v[194:195]
	s_mov_b32 m0, s10
	s_nop 0
	global_load_lds_dwordx4 v[186:187], off
	v_lshl_add_u64 v[186:187], s[46:47], 0, v[128:129]
	s_add_i32 m0, s10, 0x2000
	s_nop 0
	global_load_lds_dwordx4 v[186:187], off
	v_lshl_add_u64 v[186:187], v[242:243], 0, s[48:49]
	s_mov_b32 m0, s45
	s_nop 0
	global_load_lds_dwordx4 v[186:187], off
	v_lshl_add_u64 v[186:187], v[244:245], 0, s[48:49]
	s_mov_b32 m0, s60
	s_nop 0
	global_load_lds_dwordx4 v[186:187], off
	s_waitcnt vmcnt(8)
	s_waitcnt lgkmcnt(0)
	s_barrier
	s_setprio 1
	s_waitcnt lgkmcnt(0)
	v_mfma_f32_16x16x32_bf16 v[60:63], v[140:143], v[174:177], v[60:63]
	v_mfma_f32_16x16x32_bf16 v[56:59], v[150:153], v[174:177], v[56:59]
	v_mfma_f32_16x16x32_bf16 v[44:47], v[140:143], v[182:185], v[44:47]
	v_mfma_f32_16x16x32_bf16 v[40:43], v[150:153], v[182:185], v[40:43]
	v_mfma_f32_16x16x32_bf16 v[28:31], v[140:143], v[212:215], v[28:31]
	v_mfma_f32_16x16x32_bf16 v[24:27], v[150:153], v[212:215], v[24:27]
	v_mfma_f32_16x16x32_bf16 v[12:15], v[140:143], v[232:235], v[12:15]
	v_mfma_f32_16x16x32_bf16 v[8:11], v[150:153], v[232:235], v[8:11]
	v_mfma_f32_16x16x32_bf16 v[60:63], v[146:149], v[178:181], v[60:63]
	v_mfma_f32_16x16x32_bf16 v[56:59], v[154:157], v[178:181], v[56:59]
	v_mfma_f32_16x16x32_bf16 v[44:47], v[146:149], v[208:211], v[44:47]
	v_mfma_f32_16x16x32_bf16 v[40:43], v[154:157], v[208:211], v[40:43]
	v_mfma_f32_16x16x32_bf16 v[28:31], v[146:149], v[228:231], v[28:31]
	v_mfma_f32_16x16x32_bf16 v[24:27], v[154:157], v[228:231], v[24:27]
	v_mfma_f32_16x16x32_bf16 v[12:15], v[146:149], v[236:239], v[12:15]
	v_mfma_f32_16x16x32_bf16 v[8:11], v[154:157], v[236:239], v[8:11]
	s_setprio 0
	s_setprio 1
	v_mfma_f32_16x16x32_bf16 v[52:55], v[158:161], v[174:177], v[52:55]
	v_mfma_f32_16x16x32_bf16 v[48:51], v[166:169], v[174:177], v[48:51]
	v_mfma_f32_16x16x32_bf16 v[36:39], v[158:161], v[182:185], v[36:39]
	v_mfma_f32_16x16x32_bf16 v[32:35], v[166:169], v[182:185], v[32:35]
	v_mfma_f32_16x16x32_bf16 v[20:23], v[158:161], v[212:215], v[20:23]
	v_mfma_f32_16x16x32_bf16 v[16:19], v[166:169], v[212:215], v[16:19]
	v_mfma_f32_16x16x32_bf16 v[4:7], v[158:161], v[232:235], v[4:7]
	v_mfma_f32_16x16x32_bf16 v[0:3], v[166:169], v[232:235], v[0:3]
	v_mfma_f32_16x16x32_bf16 v[52:55], v[162:165], v[178:181], v[52:55]
	v_mfma_f32_16x16x32_bf16 v[48:51], v[170:173], v[178:181], v[48:51]
	v_mfma_f32_16x16x32_bf16 v[36:39], v[162:165], v[208:211], v[36:39]
	v_mfma_f32_16x16x32_bf16 v[32:35], v[170:173], v[208:211], v[32:35]
	v_mfma_f32_16x16x32_bf16 v[20:23], v[162:165], v[228:231], v[20:23]
	v_mfma_f32_16x16x32_bf16 v[16:19], v[170:173], v[228:231], v[16:19]
	v_mfma_f32_16x16x32_bf16 v[4:7], v[162:165], v[236:239], v[4:7]
	v_mfma_f32_16x16x32_bf16 v[0:3], v[170:173], v[236:239], v[0:3]
	s_setprio 0
	s_barrier
	s_add_i32 s78, s78, 2
	s_add_u32 s35, s35, 0x100
	s_addc_u32 s73, s73, 0
	s_cmp_gt_u32 s78, 29
	s_mov_b64 s[90:91], s[0:1]
	s_cbranch_scc0 .LBB0_1020
	s_branch .Lgemm3_exit

.Lgemm3_exit:
	s_and_b64 vcc, exec, s[64:65]
	s_cbranch_vccz .LBB0_1023
	s_barrier

.LBB0_1059:
	s_ashr_i32 s73, s72, 31
	s_lshl_b64 s[34:35], s[72:73], 20
	s_add_u32 s66, s67, s34
	v_readlane_b32 s9, v255, 54
	s_addc_u32 s67, s9, s35
	s_and_b64 s[0:1], s[0:1], exec
	s_cselect_b32 s9, s67, s47
	s_cselect_b32 s34, s66, s46
	s_add_u32 s35, s46, 0x100
	s_addc_u32 s73, s47, 0
	s_mov_b32 s78, -2
	s_waitcnt lgkmcnt(0)
	s_waitcnt vmcnt(0)
.Lgemm4_peel:
	s_add_u32 s0, s90, 0x100
	s_addc_u32 s1, s91, 0
	s_add_i32 s10, 0, 0x10000
	s_cmp_eq_u32 s78, 28
	s_cselect_b32 vcc_hi, s75, s1
	s_cselect_b32 vcc_lo, s74, s0
	v_add_u32_e32 v144, s10, v146
	s_cselect_b32 s47, s9, s73
	s_cselect_b32 s46, s34, s35
	s_add_i32 s33, 0, 0x14000
	ds_read_b128 v[140:143], v144
	ds_read_b128 v[148:151], v144 offset:1024
	ds_read_b128 v[152:155], v144 offset:2048
	ds_read_b128 v[156:159], v144 offset:3072
	v_add_u32_e32 v144, s33, v146
	ds_read_b128 v[160:163], v144
	ds_read_b128 v[164:167], v144 offset:1024
	ds_read_b128 v[168:171], v144 offset:2048
	ds_read_b128 v[172:175], v144 offset:3072
	v_lshl_add_u64 v[144:145], s[90:91], 0, v[136:137]
	s_add_i32 m0, s11, 0xc000
	ds_read_b128 v[176:179], v147
	ds_read_b128 v[180:183], v147 offset:1024
	ds_read_b128 v[184:187], v147 offset:2048
	ds_read_b128 v[208:211], v147 offset:3072
	ds_read_b128 v[212:215], v147 offset:4096
	ds_read_b128 v[228:231], v147 offset:5120
	ds_read_b128 v[232:235], v147 offset:6144
	ds_read_b128 v[236:239], v147 offset:7168
	global_load_lds_dwordx4 v[144:145], off
	v_lshl_add_u64 v[144:145], s[90:91], 0, v[138:139]
	s_add_i32 m0, s11, 0xe000
	s_nop 0
	global_load_lds_dwordx4 v[144:145], off
	s_waitcnt vmcnt(8)
	s_waitcnt lgkmcnt(0)
	s_barrier
	s_setprio 1
	s_waitcnt lgkmcnt(0)
	v_mfma_f32_16x16x32_bf16 v[124:127], v[140:143], v[176:179], 0
	v_mfma_f32_16x16x32_bf16 v[120:123], v[152:155], v[176:179], 0
	v_mfma_f32_16x16x32_bf16 v[108:111], v[140:143], v[184:187], 0
	v_mfma_f32_16x16x32_bf16 v[104:107], v[152:155], v[184:187], 0
	v_mfma_f32_16x16x32_bf16 v[92:95], v[140:143], v[212:215], 0
	v_mfma_f32_16x16x32_bf16 v[88:91], v[152:155], v[212:215], 0
	v_mfma_f32_16x16x32_bf16 v[76:79], v[140:143], v[232:235], 0
	v_mfma_f32_16x16x32_bf16 v[72:75], v[152:155], v[232:235], 0
	v_mfma_f32_16x16x32_bf16 v[124:127], v[148:151], v[180:183], v[124:127]
	v_mfma_f32_16x16x32_bf16 v[120:123], v[156:159], v[180:183], v[120:123]
	v_mfma_f32_16x16x32_bf16 v[108:111], v[148:151], v[208:211], v[108:111]
	v_mfma_f32_16x16x32_bf16 v[104:107], v[156:159], v[208:211], v[104:107]
	v_mfma_f32_16x16x32_bf16 v[92:95], v[148:151], v[228:231], v[92:95]
	v_mfma_f32_16x16x32_bf16 v[88:91], v[156:159], v[228:231], v[88:91]
	v_mfma_f32_16x16x32_bf16 v[76:79], v[148:151], v[236:239], v[76:79]
	v_mfma_f32_16x16x32_bf16 v[72:75], v[156:159], v[236:239], v[72:75]
	s_setprio 0
	s_setprio 1
	v_mfma_f32_16x16x32_bf16 v[116:119], v[160:163], v[176:179], 0
	v_mfma_f32_16x16x32_bf16 v[112:115], v[168:171], v[176:179], 0
	v_mfma_f32_16x16x32_bf16 v[100:103], v[160:163], v[184:187], 0
	v_mfma_f32_16x16x32_bf16 v[96:99], v[168:171], v[184:187], 0
	v_mfma_f32_16x16x32_bf16 v[84:87], v[160:163], v[212:215], 0
	v_mfma_f32_16x16x32_bf16 v[80:83], v[168:171], v[212:215], 0
	v_mfma_f32_16x16x32_bf16 v[68:71], v[160:163], v[232:235], 0
	v_mfma_f32_16x16x32_bf16 v[64:67], v[168:171], v[232:235], 0
	v_mfma_f32_16x16x32_bf16 v[116:119], v[164:167], v[180:183], v[116:119]
	v_mfma_f32_16x16x32_bf16 v[112:115], v[172:175], v[180:183], v[112:115]
	v_mfma_f32_16x16x32_bf16 v[100:103], v[164:167], v[208:211], v[100:103]
	v_mfma_f32_16x16x32_bf16 v[96:99], v[172:175], v[208:211], v[96:99]
	v_mfma_f32_16x16x32_bf16 v[84:87], v[164:167], v[228:231], v[84:87]
	v_mfma_f32_16x16x32_bf16 v[80:83], v[172:175], v[228:231], v[80:83]
	v_mfma_f32_16x16x32_bf16 v[68:71], v[164:167], v[236:239], v[68:71]
	v_mfma_f32_16x16x32_bf16 v[64:67], v[172:175], v[236:239], v[64:67]
	s_setprio 0
	s_barrier
	s_add_i32 s10, s10, s3
	v_lshl_add_u64 v[144:145], s[46:47], 0, v[194:195]
	s_mov_b32 m0, s10
	ds_read_b128 v[176:179], v147 offset:16384
	ds_read_b128 v[180:183], v147 offset:17408
	ds_read_b128 v[184:187], v147 offset:18432
	ds_read_b128 v[208:211], v147 offset:19456
	ds_read_b128 v[212:215], v147 offset:20480
	ds_read_b128 v[228:231], v147 offset:21504
	ds_read_b128 v[232:235], v147 offset:22528
	ds_read_b128 v[236:239], v147 offset:23552
	global_load_lds_dwordx4 v[144:145], off
	s_add_i32 m0, s10, 0x2000
	s_add_u32 s90, s46, 0x80000
	v_lshl_add_u64 v[240:241], s[46:47], 0, v[128:129]
	s_addc_u32 s91, s47, 0
	s_add_i32 s10, s33, s3
	global_load_lds_dwordx4 v[240:241], off
	v_lshl_add_u64 v[242:243], s[90:91], 0, v[194:195]
	s_mov_b32 m0, s10
	v_lshl_add_u64 v[244:245], vcc, 0, v[130:131]
	global_load_lds_dwordx4 v[242:243], off
	v_lshl_add_u64 v[242:243], s[90:91], 0, v[128:129]
	s_add_i32 m0, s10, 0x2000
	s_nop 0
	global_load_lds_dwordx4 v[242:243], off
	v_lshl_add_u64 v[242:243], vcc, 0, v[132:133]
	s_mov_b32 m0, s11
	s_nop 0
	global_load_lds_dwordx4 v[242:243], off
	s_mov_b32 m0, s12
	s_nop 0
	global_load_lds_dwordx4 v[244:245], off
	s_waitcnt vmcnt(8)
	s_waitcnt lgkmcnt(0)
	s_barrier
	s_setprio 1
	s_waitcnt lgkmcnt(0)
	v_mfma_f32_16x16x32_bf16 v[60:63], v[140:143], v[176:179], 0
	v_mfma_f32_16x16x32_bf16 v[56:59], v[152:155], v[176:179], 0
	v_mfma_f32_16x16x32_bf16 v[44:47], v[140:143], v[184:187], 0
	v_mfma_f32_16x16x32_bf16 v[40:43], v[152:155], v[184:187], 0
	v_mfma_f32_16x16x32_bf16 v[28:31], v[140:143], v[212:215], 0
	v_mfma_f32_16x16x32_bf16 v[24:27], v[152:155], v[212:215], 0
	v_mfma_f32_16x16x32_bf16 v[12:15], v[140:143], v[232:235], 0
	v_mfma_f32_16x16x32_bf16 v[8:11], v[152:155], v[232:235], 0
	v_mfma_f32_16x16x32_bf16 v[60:63], v[148:151], v[180:183], v[60:63]
	v_mfma_f32_16x16x32_bf16 v[56:59], v[156:159], v[180:183], v[56:59]
	v_mfma_f32_16x16x32_bf16 v[44:47], v[148:151], v[208:211], v[44:47]
	v_mfma_f32_16x16x32_bf16 v[40:43], v[156:159], v[208:211], v[40:43]
	v_mfma_f32_16x16x32_bf16 v[28:31], v[148:151], v[228:231], v[28:31]
	v_mfma_f32_16x16x32_bf16 v[24:27], v[156:159], v[228:231], v[24:27]
	v_mfma_f32_16x16x32_bf16 v[12:15], v[148:151], v[236:239], v[12:15]
	v_mfma_f32_16x16x32_bf16 v[8:11], v[156:159], v[236:239], v[8:11]
	s_setprio 0
	s_setprio 1
	v_mfma_f32_16x16x32_bf16 v[52:55], v[160:163], v[176:179], 0
	v_mfma_f32_16x16x32_bf16 v[48:51], v[168:171], v[176:179], 0
	v_mfma_f32_16x16x32_bf16 v[36:39], v[160:163], v[184:187], 0
	v_mfma_f32_16x16x32_bf16 v[32:35], v[168:171], v[184:187], 0
	v_mfma_f32_16x16x32_bf16 v[20:23], v[160:163], v[212:215], 0
	v_mfma_f32_16x16x32_bf16 v[16:19], v[168:171], v[212:215], 0
	v_mfma_f32_16x16x32_bf16 v[4:7], v[160:163], v[232:235], 0
	v_mfma_f32_16x16x32_bf16 v[0:3], v[168:171], v[232:235], 0
	v_mfma_f32_16x16x32_bf16 v[52:55], v[164:167], v[180:183], v[52:55]
	v_mfma_f32_16x16x32_bf16 v[48:51], v[172:175], v[180:183], v[48:51]
	v_mfma_f32_16x16x32_bf16 v[36:39], v[164:167], v[208:211], v[36:39]
	v_mfma_f32_16x16x32_bf16 v[32:35], v[172:175], v[208:211], v[32:35]
	v_mfma_f32_16x16x32_bf16 v[20:23], v[164:167], v[228:231], v[20:23]
	v_mfma_f32_16x16x32_bf16 v[16:19], v[172:175], v[228:231], v[16:19]
	v_mfma_f32_16x16x32_bf16 v[4:7], v[164:167], v[236:239], v[4:7]
	v_mfma_f32_16x16x32_bf16 v[0:3], v[172:175], v[236:239], v[0:3]
	s_setprio 0
	s_barrier
	s_add_i32 s10, 0, 0x18000
	s_add_i32 s33, 0, 0x1c000
	v_add_u32_e32 v156, s10, v146
	v_add_u32_e32 v172, s33, v146
	ds_read_b128 v[140:143], v156
	ds_read_b128 v[148:151], v156 offset:1024
	ds_read_b128 v[152:155], v156 offset:2048
	ds_read_b128 v[156:159], v156 offset:3072
	ds_read_b128 v[160:163], v172
	ds_read_b128 v[164:167], v172 offset:1024
	ds_read_b128 v[168:171], v172 offset:2048
	ds_read_b128 v[172:175], v172 offset:3072
	s_add_u32 s90, vcc_lo, 0x160000
	s_addc_u32 s91, vcc_hi, 0
	s_mov_b32 m0, s16
	v_lshl_add_u64 v[246:247], s[90:91], 0, v[132:133]
	ds_read_b128 v[176:179], v147 offset:32768
	ds_read_b128 v[180:183], v147 offset:33792
	ds_read_b128 v[184:187], v147 offset:34816
	ds_read_b128 v[208:211], v147 offset:35840
	ds_read_b128 v[212:215], v147 offset:36864
	ds_read_b128 v[228:231], v147 offset:37888
	ds_read_b128 v[232:235], v147 offset:38912
	ds_read_b128 v[236:239], v147 offset:39936
	global_load_lds_dwordx4 v[246:247], off
	v_lshl_add_u64 v[246:247], s[90:91], 0, v[130:131]
	s_mov_b32 m0, s17
	s_nop 0
	global_load_lds_dwordx4 v[246:247], off
	s_waitcnt vmcnt(8)
	s_waitcnt lgkmcnt(0)
	s_barrier
	s_setprio 1
	s_waitcnt lgkmcnt(0)
	v_mfma_f32_16x16x32_bf16 v[124:127], v[140:143], v[176:179], v[124:127]
	v_mfma_f32_16x16x32_bf16 v[120:123], v[152:155], v[176:179], v[120:123]
	v_mfma_f32_16x16x32_bf16 v[108:111], v[140:143], v[184:187], v[108:111]
	v_mfma_f32_16x16x32_bf16 v[104:107], v[152:155], v[184:187], v[104:107]
	v_mfma_f32_16x16x32_bf16 v[92:95], v[140:143], v[212:215], v[92:95]
	v_mfma_f32_16x16x32_bf16 v[88:91], v[152:155], v[212:215], v[88:91]
	v_mfma_f32_16x16x32_bf16 v[76:79], v[140:143], v[232:235], v[76:79]
	v_mfma_f32_16x16x32_bf16 v[72:75], v[152:155], v[232:235], v[72:75]
	v_mfma_f32_16x16x32_bf16 v[124:127], v[148:151], v[180:183], v[124:127]
	v_mfma_f32_16x16x32_bf16 v[120:123], v[156:159], v[180:183], v[120:123]
	v_mfma_f32_16x16x32_bf16 v[108:111], v[148:151], v[208:211], v[108:111]
	v_mfma_f32_16x16x32_bf16 v[104:107], v[156:159], v[208:211], v[104:107]
	v_mfma_f32_16x16x32_bf16 v[92:95], v[148:151], v[228:231], v[92:95]
	v_mfma_f32_16x16x32_bf16 v[88:91], v[156:159], v[228:231], v[88:91]
	v_mfma_f32_16x16x32_bf16 v[76:79], v[148:151], v[236:239], v[76:79]
	v_mfma_f32_16x16x32_bf16 v[72:75], v[156:159], v[236:239], v[72:75]
	s_setprio 0
	s_setprio 1
	v_mfma_f32_16x16x32_bf16 v[116:119], v[160:163], v[176:179], v[116:119]
	v_mfma_f32_16x16x32_bf16 v[112:115], v[168:171], v[176:179], v[112:115]
	v_mfma_f32_16x16x32_bf16 v[100:103], v[160:163], v[184:187], v[100:103]
	v_mfma_f32_16x16x32_bf16 v[96:99], v[168:171], v[184:187], v[96:99]
	v_mfma_f32_16x16x32_bf16 v[84:87], v[160:163], v[212:215], v[84:87]
	v_mfma_f32_16x16x32_bf16 v[80:83], v[168:171], v[212:215], v[80:83]
	v_mfma_f32_16x16x32_bf16 v[68:71], v[160:163], v[232:235], v[68:71]
	v_mfma_f32_16x16x32_bf16 v[64:67], v[168:171], v[232:235], v[64:67]
	v_mfma_f32_16x16x32_bf16 v[116:119], v[164:167], v[180:183], v[116:119]
	v_mfma_f32_16x16x32_bf16 v[112:115], v[172:175], v[180:183], v[112:115]
	v_mfma_f32_16x16x32_bf16 v[100:103], v[164:167], v[208:211], v[100:103]
	v_mfma_f32_16x16x32_bf16 v[96:99], v[172:175], v[208:211], v[96:99]
	v_mfma_f32_16x16x32_bf16 v[84:87], v[164:167], v[228:231], v[84:87]
	v_mfma_f32_16x16x32_bf16 v[80:83], v[172:175], v[228:231], v[80:83]
	v_mfma_f32_16x16x32_bf16 v[68:71], v[164:167], v[236:239], v[68:71]
	v_mfma_f32_16x16x32_bf16 v[64:67], v[172:175], v[236:239], v[64:67]
	s_setprio 0
	s_barrier
	s_add_i32 s10, s10, s3
	v_lshl_add_u64 v[144:145], v[144:145], 0, s[48:49]
	s_mov_b32 m0, s10
	ds_read_b128 v[176:179], v147 offset:49152
	ds_read_b128 v[180:183], v147 offset:50176
	ds_read_b128 v[184:187], v147 offset:51200
	ds_read_b128 v[208:211], v147 offset:52224
	ds_read_b128 v[212:215], v147 offset:53248
	ds_read_b128 v[228:231], v147 offset:54272
	ds_read_b128 v[232:235], v147 offset:55296
	ds_read_b128 v[236:239], v147 offset:56320
	global_load_lds_dwordx4 v[144:145], off
	s_add_i32 m0, s10, 0x2000
	s_add_u32 s46, s46, 0x80080
	v_lshl_add_u64 v[144:145], v[240:241], 0, s[48:49]
	s_addc_u32 s47, s47, 0
	s_add_i32 s10, s33, s3
	global_load_lds_dwordx4 v[144:145], off
	v_lshl_add_u64 v[144:145], s[46:47], 0, v[194:195]
	s_mov_b32 m0, s10
	s_nop 0
	global_load_lds_dwordx4 v[144:145], off
	v_lshl_add_u64 v[144:145], s[46:47], 0, v[128:129]
	s_add_i32 m0, s10, 0x2000
	s_nop 0
	global_load_lds_dwordx4 v[144:145], off
	v_lshl_add_u64 v[144:145], v[242:243], 0, s[48:49]
	s_mov_b32 m0, s45
	s_nop 0
	global_load_lds_dwordx4 v[144:145], off
	v_lshl_add_u64 v[144:145], v[244:245], 0, s[48:49]
	s_mov_b32 m0, s60
	s_nop 0
	global_load_lds_dwordx4 v[144:145], off
	s_waitcnt vmcnt(8)
	s_waitcnt lgkmcnt(0)
	s_barrier
	s_setprio 1
	s_waitcnt lgkmcnt(0)
	v_mfma_f32_16x16x32_bf16 v[60:63], v[140:143], v[176:179], v[60:63]
	v_mfma_f32_16x16x32_bf16 v[56:59], v[152:155], v[176:179], v[56:59]
	v_mfma_f32_16x16x32_bf16 v[44:47], v[140:143], v[184:187], v[44:47]
	v_mfma_f32_16x16x32_bf16 v[40:43], v[152:155], v[184:187], v[40:43]
	v_mfma_f32_16x16x32_bf16 v[28:31], v[140:143], v[212:215], v[28:31]
	v_mfma_f32_16x16x32_bf16 v[24:27], v[152:155], v[212:215], v[24:27]
	v_mfma_f32_16x16x32_bf16 v[12:15], v[140:143], v[232:235], v[12:15]
	v_mfma_f32_16x16x32_bf16 v[8:11], v[152:155], v[232:235], v[8:11]
	v_mfma_f32_16x16x32_bf16 v[60:63], v[148:151], v[180:183], v[60:63]
	v_mfma_f32_16x16x32_bf16 v[56:59], v[156:159], v[180:183], v[56:59]
	v_mfma_f32_16x16x32_bf16 v[44:47], v[148:151], v[208:211], v[44:47]
	v_mfma_f32_16x16x32_bf16 v[40:43], v[156:159], v[208:211], v[40:43]
	v_mfma_f32_16x16x32_bf16 v[28:31], v[148:151], v[228:231], v[28:31]
	v_mfma_f32_16x16x32_bf16 v[24:27], v[156:159], v[228:231], v[24:27]
	v_mfma_f32_16x16x32_bf16 v[12:15], v[148:151], v[236:239], v[12:15]
	v_mfma_f32_16x16x32_bf16 v[8:11], v[156:159], v[236:239], v[8:11]
	s_setprio 0
	s_setprio 1
	v_mfma_f32_16x16x32_bf16 v[52:55], v[160:163], v[176:179], v[52:55]
	v_mfma_f32_16x16x32_bf16 v[48:51], v[168:171], v[176:179], v[48:51]
	v_mfma_f32_16x16x32_bf16 v[36:39], v[160:163], v[184:187], v[36:39]
	v_mfma_f32_16x16x32_bf16 v[32:35], v[168:171], v[184:187], v[32:35]
	v_mfma_f32_16x16x32_bf16 v[20:23], v[160:163], v[212:215], v[20:23]
	v_mfma_f32_16x16x32_bf16 v[16:19], v[168:171], v[212:215], v[16:19]
	v_mfma_f32_16x16x32_bf16 v[4:7], v[160:163], v[232:235], v[4:7]
	v_mfma_f32_16x16x32_bf16 v[0:3], v[168:171], v[232:235], v[0:3]
	v_mfma_f32_16x16x32_bf16 v[52:55], v[164:167], v[180:183], v[52:55]
	v_mfma_f32_16x16x32_bf16 v[48:51], v[172:175], v[180:183], v[48:51]
	v_mfma_f32_16x16x32_bf16 v[36:39], v[164:167], v[208:211], v[36:39]
	v_mfma_f32_16x16x32_bf16 v[32:35], v[172:175], v[208:211], v[32:35]
	v_mfma_f32_16x16x32_bf16 v[20:23], v[164:167], v[228:231], v[20:23]
	v_mfma_f32_16x16x32_bf16 v[16:19], v[172:175], v[228:231], v[16:19]
	v_mfma_f32_16x16x32_bf16 v[4:7], v[164:167], v[236:239], v[4:7]
	v_mfma_f32_16x16x32_bf16 v[0:3], v[172:175], v[236:239], v[0:3]
	s_setprio 0
	s_barrier
	s_add_i32 s78, s78, 2
	s_add_u32 s35, s35, 0x100
	s_addc_u32 s73, s73, 0
	s_cmp_gt_u32 s78, 29
	s_mov_b64 s[90:91], s[0:1]
	s_cbranch_scc0 .LBB0_1060
	s_branch .Lgemm4_exit

.Lgemm4_exit:
	s_mov_b64 s[56:57], s[80:81]
	s_mov_b64 s[58:59], s[82:83]
	s_and_b64 vcc, exec, s[64:65]
	s_cbranch_vccz .LBB0_1063
	s_barrier
